# adds scalar-base LDS-DMA addressing in all GEMM K-loops on top of the moved barrier and attention changes
# baseline (speedup 1.0000x reference)
.LBB0_168:
	s_add_u32 s46, s66, 0xfff80080
	s_addc_u32 s47, s67, -1
	s_add_i32 s62, 0, 0x10000
	s_cmp_eq_u32 s82, 28
	s_cselect_b32 s69, s17, s47
	s_cselect_b32 s68, s65, s46
	v_add_u32_e32 v143, s62, v140
	s_cselect_b32 s61, s13, s81
	s_cselect_b32 s60, s79, s80
	s_add_i32 s63, 0, 0x14000
	ds_read_b128 v[144:147], v143
	ds_read_b128 v[148:151], v143 offset:1024
	ds_read_b128 v[152:155], v143 offset:2048
	ds_read_b128 v[156:159], v143 offset:3072
	v_add_u32_e32 v143, s63, v140
	ds_read_b128 v[160:163], v143
	ds_read_b128 v[178:181], v143 offset:1024
	ds_read_b128 v[182:185], v143 offset:2048
	ds_read_b128 v[186:189], v143 offset:3072
	s_add_i32 m0, s19, 0xc000
	ds_read_b128 v[206:209], v142
	ds_read_b128 v[210:213], v142 offset:1024
	ds_read_b128 v[214:217], v142 offset:2048
	ds_read_b128 v[218:221], v142 offset:3072
	ds_read_b128 v[222:225], v142 offset:4096
	ds_read_b128 v[226:229], v142 offset:5120
	ds_read_b128 v[230:233], v142 offset:6144
	ds_read_b128 v[234:237], v142 offset:7168
	global_load_lds_dwordx4 v136, s[66:67]
	s_add_i32 m0, s19, 0xe000
	s_nop 0
	global_load_lds_dwordx4 v138, s[66:67]
	s_waitcnt vmcnt(8)
	s_waitcnt lgkmcnt(0)
	s_setprio 1
	s_waitcnt lgkmcnt(0)
	v_mfma_f32_16x16x32_bf16 v[126:129], v[144:147], v[206:209], v[126:129]
	v_mfma_f32_16x16x32_bf16 v[122:125], v[152:155], v[206:209], v[122:125]
	v_mfma_f32_16x16x32_bf16 v[118:121], v[144:147], v[214:217], v[118:121]
	v_mfma_f32_16x16x32_bf16 v[114:117], v[152:155], v[214:217], v[114:117]
	s_barrier
	v_mfma_f32_16x16x32_bf16 v[102:105], v[144:147], v[222:225], v[102:105]
	v_mfma_f32_16x16x32_bf16 v[98:101], v[152:155], v[222:225], v[98:101]
	v_mfma_f32_16x16x32_bf16 v[86:89], v[144:147], v[230:233], v[86:89]
	v_mfma_f32_16x16x32_bf16 v[82:85], v[152:155], v[230:233], v[82:85]
	v_mfma_f32_16x16x32_bf16 v[126:129], v[148:151], v[210:213], v[126:129]
	v_mfma_f32_16x16x32_bf16 v[122:125], v[156:159], v[210:213], v[122:125]
	v_mfma_f32_16x16x32_bf16 v[118:121], v[148:151], v[218:221], v[118:121]
	v_mfma_f32_16x16x32_bf16 v[114:117], v[156:159], v[218:221], v[114:117]
	v_mfma_f32_16x16x32_bf16 v[102:105], v[148:151], v[226:229], v[102:105]
	v_mfma_f32_16x16x32_bf16 v[98:101], v[156:159], v[226:229], v[98:101]
	v_mfma_f32_16x16x32_bf16 v[86:89], v[148:151], v[234:237], v[86:89]
	v_mfma_f32_16x16x32_bf16 v[82:85], v[156:159], v[234:237], v[82:85]
	s_setprio 0
	s_setprio 1
	v_mfma_f32_16x16x32_bf16 v[110:113], v[160:163], v[206:209], v[110:113]
	v_mfma_f32_16x16x32_bf16 v[106:109], v[182:185], v[206:209], v[106:109]
	v_mfma_f32_16x16x32_bf16 v[94:97], v[160:163], v[214:217], v[94:97]
	v_mfma_f32_16x16x32_bf16 v[90:93], v[182:185], v[214:217], v[90:93]
	v_mfma_f32_16x16x32_bf16 v[78:81], v[160:163], v[222:225], v[78:81]
	v_mfma_f32_16x16x32_bf16 v[74:77], v[182:185], v[222:225], v[74:77]
	v_mfma_f32_16x16x32_bf16 v[70:73], v[160:163], v[230:233], v[70:73]
	v_mfma_f32_16x16x32_bf16 v[66:69], v[182:185], v[230:233], v[66:69]
	v_mfma_f32_16x16x32_bf16 v[110:113], v[178:181], v[210:213], v[110:113]
	v_mfma_f32_16x16x32_bf16 v[106:109], v[186:189], v[210:213], v[106:109]
	v_mfma_f32_16x16x32_bf16 v[94:97], v[178:181], v[218:221], v[94:97]
	v_mfma_f32_16x16x32_bf16 v[90:93], v[186:189], v[218:221], v[90:93]
	v_mfma_f32_16x16x32_bf16 v[78:81], v[178:181], v[226:229], v[78:81]
	v_mfma_f32_16x16x32_bf16 v[74:77], v[186:189], v[226:229], v[74:77]
	v_mfma_f32_16x16x32_bf16 v[70:73], v[178:181], v[234:237], v[70:73]
	v_mfma_f32_16x16x32_bf16 v[66:69], v[186:189], v[234:237], v[66:69]
	s_setprio 0
	s_barrier
	s_add_i32 s46, s62, s71
	s_mov_b32 m0, s46
	ds_read_b128 v[206:209], v142 offset:16384
	ds_read_b128 v[210:213], v142 offset:17408
	ds_read_b128 v[214:217], v142 offset:18432
	ds_read_b128 v[218:221], v142 offset:19456
	ds_read_b128 v[222:225], v142 offset:20480
	ds_read_b128 v[226:229], v142 offset:21504
	ds_read_b128 v[230:233], v142 offset:22528
	ds_read_b128 v[234:237], v142 offset:23552
	global_load_lds_dwordx4 v166, s[60:61]
	s_add_i32 m0, s46, 0x2000
	s_add_u32 s46, s60, 0x80000
	v_lshl_add_u64 v[242:243], s[60:61], 0, v[130:131]
	s_addc_u32 s47, s61, 0
	s_add_i32 s62, s63, s71
	global_load_lds_dwordx4 v130, s[60:61]
	s_mov_b32 m0, s62
	s_nop 0
	global_load_lds_dwordx4 v166, s[46:47]
	s_add_i32 m0, s62, 0x2000
	s_nop 0
	global_load_lds_dwordx4 v130, s[46:47]
	s_mov_b32 m0, s19
	s_nop 0
	global_load_lds_dwordx4 v134, s[68:69]
	s_mov_b32 m0, s73
	s_nop 0
	global_load_lds_dwordx4 v132, s[68:69]
	s_waitcnt vmcnt(8)
	s_waitcnt lgkmcnt(0)
	s_setprio 1
	s_waitcnt lgkmcnt(0)
	v_mfma_f32_16x16x32_bf16 v[62:65], v[144:147], v[206:209], v[62:65]
	v_mfma_f32_16x16x32_bf16 v[58:61], v[152:155], v[206:209], v[58:61]
	v_mfma_f32_16x16x32_bf16 v[54:57], v[144:147], v[214:217], v[54:57]
	v_mfma_f32_16x16x32_bf16 v[50:53], v[152:155], v[214:217], v[50:53]
	s_barrier
	v_mfma_f32_16x16x32_bf16 v[38:41], v[144:147], v[222:225], v[38:41]
	v_mfma_f32_16x16x32_bf16 v[34:37], v[152:155], v[222:225], v[34:37]
	v_mfma_f32_16x16x32_bf16 v[22:25], v[144:147], v[230:233], v[22:25]
	v_mfma_f32_16x16x32_bf16 v[18:21], v[152:155], v[230:233], v[18:21]
	v_mfma_f32_16x16x32_bf16 v[62:65], v[148:151], v[210:213], v[62:65]
	v_mfma_f32_16x16x32_bf16 v[58:61], v[156:159], v[210:213], v[58:61]
	v_mfma_f32_16x16x32_bf16 v[54:57], v[148:151], v[218:221], v[54:57]
	v_mfma_f32_16x16x32_bf16 v[50:53], v[156:159], v[218:221], v[50:53]
	v_mfma_f32_16x16x32_bf16 v[38:41], v[148:151], v[226:229], v[38:41]
	v_mfma_f32_16x16x32_bf16 v[34:37], v[156:159], v[226:229], v[34:37]
	v_mfma_f32_16x16x32_bf16 v[22:25], v[148:151], v[234:237], v[22:25]
	v_mfma_f32_16x16x32_bf16 v[18:21], v[156:159], v[234:237], v[18:21]
	s_setprio 0
	s_setprio 1
	v_mfma_f32_16x16x32_bf16 v[46:49], v[160:163], v[206:209], v[46:49]
	v_mfma_f32_16x16x32_bf16 v[42:45], v[182:185], v[206:209], v[42:45]
	v_mfma_f32_16x16x32_bf16 v[30:33], v[160:163], v[214:217], v[30:33]
	v_mfma_f32_16x16x32_bf16 v[26:29], v[182:185], v[214:217], v[26:29]
	v_mfma_f32_16x16x32_bf16 v[14:17], v[160:163], v[222:225], v[14:17]
	v_mfma_f32_16x16x32_bf16 v[10:13], v[182:185], v[222:225], v[10:13]
	v_mfma_f32_16x16x32_bf16 v[6:9], v[160:163], v[230:233], v[6:9]
	v_mfma_f32_16x16x32_bf16 v[2:5], v[182:185], v[230:233], v[2:5]
	v_mfma_f32_16x16x32_bf16 v[46:49], v[178:181], v[210:213], v[46:49]
	v_mfma_f32_16x16x32_bf16 v[42:45], v[186:189], v[210:213], v[42:45]
	v_mfma_f32_16x16x32_bf16 v[30:33], v[178:181], v[218:221], v[30:33]
	v_mfma_f32_16x16x32_bf16 v[26:29], v[186:189], v[218:221], v[26:29]
	v_mfma_f32_16x16x32_bf16 v[14:17], v[178:181], v[226:229], v[14:17]
	v_mfma_f32_16x16x32_bf16 v[10:13], v[186:189], v[226:229], v[10:13]
	v_mfma_f32_16x16x32_bf16 v[6:9], v[178:181], v[234:237], v[6:9]
	v_mfma_f32_16x16x32_bf16 v[2:5], v[186:189], v[234:237], v[2:5]
	s_setprio 0
	s_barrier
	s_add_i32 s62, 0, 0x18000
	v_add_u32_e32 v143, s62, v140
	s_add_i32 s63, 0, 0x1c000
	ds_read_b128 v[144:147], v143
	ds_read_b128 v[148:151], v143 offset:1024
	ds_read_b128 v[152:155], v143 offset:2048
	ds_read_b128 v[156:159], v143 offset:3072
	v_add_u32_e32 v143, s63, v140
	ds_read_b128 v[160:163], v143
	ds_read_b128 v[178:181], v143 offset:1024
	ds_read_b128 v[182:185], v143 offset:2048
	ds_read_b128 v[186:189], v143 offset:3072
	s_add_u32 s46, s68, 0x80000
	s_addc_u32 s47, s69, 0
	s_mov_b32 m0, s74
	ds_read_b128 v[206:209], v142 offset:32768
	ds_read_b128 v[210:213], v142 offset:33792
	ds_read_b128 v[214:217], v142 offset:34816
	ds_read_b128 v[218:221], v142 offset:35840
	ds_read_b128 v[222:225], v142 offset:36864
	ds_read_b128 v[226:229], v142 offset:37888
	ds_read_b128 v[230:233], v142 offset:38912
	ds_read_b128 v[234:237], v142 offset:39936
	global_load_lds_dwordx4 v134, s[46:47]
	s_mov_b32 m0, s75
	s_nop 0
	global_load_lds_dwordx4 v132, s[46:47]
	s_waitcnt vmcnt(8)
	s_waitcnt lgkmcnt(0)
	s_setprio 1
	s_waitcnt lgkmcnt(0)
	v_mfma_f32_16x16x32_bf16 v[126:129], v[144:147], v[206:209], v[126:129]
	v_mfma_f32_16x16x32_bf16 v[122:125], v[152:155], v[206:209], v[122:125]
	v_mfma_f32_16x16x32_bf16 v[118:121], v[144:147], v[214:217], v[118:121]
	v_mfma_f32_16x16x32_bf16 v[114:117], v[152:155], v[214:217], v[114:117]
	s_barrier
	v_mfma_f32_16x16x32_bf16 v[102:105], v[144:147], v[222:225], v[102:105]
	v_mfma_f32_16x16x32_bf16 v[98:101], v[152:155], v[222:225], v[98:101]
	v_mfma_f32_16x16x32_bf16 v[86:89], v[144:147], v[230:233], v[86:89]
	v_mfma_f32_16x16x32_bf16 v[82:85], v[152:155], v[230:233], v[82:85]
	v_mfma_f32_16x16x32_bf16 v[126:129], v[148:151], v[210:213], v[126:129]
	v_mfma_f32_16x16x32_bf16 v[122:125], v[156:159], v[210:213], v[122:125]
	v_mfma_f32_16x16x32_bf16 v[118:121], v[148:151], v[218:221], v[118:121]
	v_mfma_f32_16x16x32_bf16 v[114:117], v[156:159], v[218:221], v[114:117]
	v_mfma_f32_16x16x32_bf16 v[102:105], v[148:151], v[226:229], v[102:105]
	v_mfma_f32_16x16x32_bf16 v[98:101], v[156:159], v[226:229], v[98:101]
	v_mfma_f32_16x16x32_bf16 v[86:89], v[148:151], v[234:237], v[86:89]
	v_mfma_f32_16x16x32_bf16 v[82:85], v[156:159], v[234:237], v[82:85]
	s_setprio 0
	s_setprio 1
	v_mfma_f32_16x16x32_bf16 v[110:113], v[160:163], v[206:209], v[110:113]
	v_mfma_f32_16x16x32_bf16 v[106:109], v[182:185], v[206:209], v[106:109]
	v_mfma_f32_16x16x32_bf16 v[94:97], v[160:163], v[214:217], v[94:97]
	v_mfma_f32_16x16x32_bf16 v[90:93], v[182:185], v[214:217], v[90:93]
	v_mfma_f32_16x16x32_bf16 v[78:81], v[160:163], v[222:225], v[78:81]
	v_mfma_f32_16x16x32_bf16 v[74:77], v[182:185], v[222:225], v[74:77]
	v_mfma_f32_16x16x32_bf16 v[70:73], v[160:163], v[230:233], v[70:73]
	v_mfma_f32_16x16x32_bf16 v[66:69], v[182:185], v[230:233], v[66:69]
	v_mfma_f32_16x16x32_bf16 v[110:113], v[178:181], v[210:213], v[110:113]
	v_mfma_f32_16x16x32_bf16 v[106:109], v[186:189], v[210:213], v[106:109]
	v_mfma_f32_16x16x32_bf16 v[94:97], v[178:181], v[218:221], v[94:97]
	v_mfma_f32_16x16x32_bf16 v[90:93], v[186:189], v[218:221], v[90:93]
	v_mfma_f32_16x16x32_bf16 v[78:81], v[178:181], v[226:229], v[78:81]
	v_mfma_f32_16x16x32_bf16 v[74:77], v[186:189], v[226:229], v[74:77]
	v_mfma_f32_16x16x32_bf16 v[70:73], v[178:181], v[234:237], v[70:73]
	v_mfma_f32_16x16x32_bf16 v[66:69], v[186:189], v[234:237], v[66:69]
	s_setprio 0
	s_barrier
	s_add_i32 s46, s62, s71
	s_mov_b32 m0, s46
	ds_read_b128 v[206:209], v142 offset:49152
	ds_read_b128 v[210:213], v142 offset:50176
	ds_read_b128 v[214:217], v142 offset:51200
	ds_read_b128 v[218:221], v142 offset:52224
	ds_read_b128 v[222:225], v142 offset:53248
	ds_read_b128 v[226:229], v142 offset:54272
	ds_read_b128 v[230:233], v142 offset:55296
	ds_read_b128 v[234:237], v142 offset:56320
	s_add_u32 s100, s60, 128
	s_addc_u32 s101, s61, 0
	global_load_lds_dwordx4 v166, s[100:101]
	s_add_i32 m0, s46, 0x2000
	s_add_u32 s46, s60, 0x80080
	v_lshl_add_u64 v[164:165], v[242:243], 0, s[42:43]
	s_addc_u32 s47, s61, 0
	s_add_i32 s60, s63, s71
	global_load_lds_dwordx4 v[164:165], off
	s_mov_b32 m0, s60
	s_nop 0
	global_load_lds_dwordx4 v166, s[46:47]
	s_add_i32 m0, s60, 0x2000
	s_nop 0
	global_load_lds_dwordx4 v130, s[46:47]
	s_mov_b32 m0, s76
	s_nop 0
	s_add_u32 s100, s68, 128
	s_addc_u32 s101, s69, 0
	global_load_lds_dwordx4 v134, s[100:101]
	s_mov_b32 m0, s77
	s_nop 0
	s_add_u32 s100, s68, 128
	s_addc_u32 s101, s69, 0
	global_load_lds_dwordx4 v132, s[100:101]
	s_waitcnt vmcnt(8)
	s_waitcnt lgkmcnt(0)
	s_setprio 1
	s_waitcnt lgkmcnt(0)
	v_mfma_f32_16x16x32_bf16 v[62:65], v[144:147], v[206:209], v[62:65]
	v_mfma_f32_16x16x32_bf16 v[58:61], v[152:155], v[206:209], v[58:61]
	v_mfma_f32_16x16x32_bf16 v[54:57], v[144:147], v[214:217], v[54:57]
	v_mfma_f32_16x16x32_bf16 v[50:53], v[152:155], v[214:217], v[50:53]
	s_barrier
	v_mfma_f32_16x16x32_bf16 v[38:41], v[144:147], v[222:225], v[38:41]
	v_mfma_f32_16x16x32_bf16 v[34:37], v[152:155], v[222:225], v[34:37]
	v_mfma_f32_16x16x32_bf16 v[22:25], v[144:147], v[230:233], v[22:25]
	v_mfma_f32_16x16x32_bf16 v[18:21], v[152:155], v[230:233], v[18:21]
	v_mfma_f32_16x16x32_bf16 v[62:65], v[148:151], v[210:213], v[62:65]
	v_mfma_f32_16x16x32_bf16 v[58:61], v[156:159], v[210:213], v[58:61]
	v_mfma_f32_16x16x32_bf16 v[54:57], v[148:151], v[218:221], v[54:57]
	v_mfma_f32_16x16x32_bf16 v[50:53], v[156:159], v[218:221], v[50:53]
	v_mfma_f32_16x16x32_bf16 v[38:41], v[148:151], v[226:229], v[38:41]
	v_mfma_f32_16x16x32_bf16 v[34:37], v[156:159], v[226:229], v[34:37]
	v_mfma_f32_16x16x32_bf16 v[22:25], v[148:151], v[234:237], v[22:25]
	v_mfma_f32_16x16x32_bf16 v[18:21], v[156:159], v[234:237], v[18:21]
	s_setprio 0
	s_setprio 1
	v_mfma_f32_16x16x32_bf16 v[46:49], v[160:163], v[206:209], v[46:49]
	v_mfma_f32_16x16x32_bf16 v[42:45], v[182:185], v[206:209], v[42:45]
	v_mfma_f32_16x16x32_bf16 v[30:33], v[160:163], v[214:217], v[30:33]
	v_mfma_f32_16x16x32_bf16 v[26:29], v[182:185], v[214:217], v[26:29]
	v_mfma_f32_16x16x32_bf16 v[14:17], v[160:163], v[222:225], v[14:17]
	v_mfma_f32_16x16x32_bf16 v[10:13], v[182:185], v[222:225], v[10:13]
	v_mfma_f32_16x16x32_bf16 v[6:9], v[160:163], v[230:233], v[6:9]
	v_mfma_f32_16x16x32_bf16 v[2:5], v[182:185], v[230:233], v[2:5]
	v_mfma_f32_16x16x32_bf16 v[46:49], v[178:181], v[210:213], v[46:49]
	v_mfma_f32_16x16x32_bf16 v[42:45], v[186:189], v[210:213], v[42:45]
	v_mfma_f32_16x16x32_bf16 v[30:33], v[178:181], v[218:221], v[30:33]
	v_mfma_f32_16x16x32_bf16 v[26:29], v[186:189], v[218:221], v[26:29]
	v_mfma_f32_16x16x32_bf16 v[14:17], v[178:181], v[226:229], v[14:17]
	v_mfma_f32_16x16x32_bf16 v[10:13], v[186:189], v[226:229], v[10:13]
	v_mfma_f32_16x16x32_bf16 v[6:9], v[178:181], v[234:237], v[6:9]
	v_mfma_f32_16x16x32_bf16 v[2:5], v[186:189], v[234:237], v[2:5]
	s_setprio 0
	s_barrier
	s_add_i32 s82, s82, 2
	s_add_u32 s66, s66, 0x100
	s_addc_u32 s67, s67, 0
	s_add_u32 s80, s80, 0x100
	s_addc_u32 s81, s81, 0
	s_cmp_gt_u32 s82, 29
	s_cbranch_scc0 .LBB0_168
	s_and_b64 vcc, exec, s[10:11]
	s_cbranch_vccz .LBB0_171
	s_barrier

.LBB0_426:
	s_add_u32 s46, s66, 0xfffe0080
	s_addc_u32 s47, s67, -1
	s_add_i32 s62, 0, 0x10000
	s_cmp_eq_u32 s84, 4
	s_cselect_b32 s69, s19, s47
	s_cselect_b32 s68, s80, s46
	v_add_u32_e32 v143, s62, v140
	s_cselect_b32 s61, s17, s83
	s_cselect_b32 s60, s81, s82
	s_add_i32 s63, 0, 0x14000
	ds_read_b128 v[144:147], v143
	ds_read_b128 v[148:151], v143 offset:1024
	ds_read_b128 v[152:155], v143 offset:2048
	ds_read_b128 v[156:159], v143 offset:3072
	v_add_u32_e32 v143, s63, v140
	ds_read_b128 v[160:163], v143
	ds_read_b128 v[178:181], v143 offset:1024
	ds_read_b128 v[182:185], v143 offset:2048
	ds_read_b128 v[186:189], v143 offset:3072
	s_add_i32 m0, s11, 0xc000
	ds_read_b128 v[206:209], v142
	ds_read_b128 v[210:213], v142 offset:1024
	ds_read_b128 v[214:217], v142 offset:2048
	ds_read_b128 v[218:221], v142 offset:3072
	ds_read_b128 v[222:225], v142 offset:4096
	ds_read_b128 v[226:229], v142 offset:5120
	ds_read_b128 v[230:233], v142 offset:6144
	ds_read_b128 v[234:237], v142 offset:7168
	global_load_lds_dwordx4 v136, s[66:67]
	s_add_i32 m0, s11, 0xe000
	s_nop 0
	global_load_lds_dwordx4 v138, s[66:67]
	s_waitcnt vmcnt(8)
	s_waitcnt lgkmcnt(0)
	s_setprio 1
	s_waitcnt lgkmcnt(0)
	v_mfma_f32_16x16x32_bf16 v[126:129], v[144:147], v[206:209], v[126:129]
	v_mfma_f32_16x16x32_bf16 v[122:125], v[152:155], v[206:209], v[122:125]
	v_mfma_f32_16x16x32_bf16 v[118:121], v[144:147], v[214:217], v[118:121]
	v_mfma_f32_16x16x32_bf16 v[114:117], v[152:155], v[214:217], v[114:117]
	s_barrier
	v_mfma_f32_16x16x32_bf16 v[102:105], v[144:147], v[222:225], v[102:105]
	v_mfma_f32_16x16x32_bf16 v[98:101], v[152:155], v[222:225], v[98:101]
	v_mfma_f32_16x16x32_bf16 v[86:89], v[144:147], v[230:233], v[86:89]
	v_mfma_f32_16x16x32_bf16 v[82:85], v[152:155], v[230:233], v[82:85]
	v_mfma_f32_16x16x32_bf16 v[126:129], v[148:151], v[210:213], v[126:129]
	v_mfma_f32_16x16x32_bf16 v[122:125], v[156:159], v[210:213], v[122:125]
	v_mfma_f32_16x16x32_bf16 v[118:121], v[148:151], v[218:221], v[118:121]
	v_mfma_f32_16x16x32_bf16 v[114:117], v[156:159], v[218:221], v[114:117]
	v_mfma_f32_16x16x32_bf16 v[102:105], v[148:151], v[226:229], v[102:105]
	v_mfma_f32_16x16x32_bf16 v[98:101], v[156:159], v[226:229], v[98:101]
	v_mfma_f32_16x16x32_bf16 v[86:89], v[148:151], v[234:237], v[86:89]
	v_mfma_f32_16x16x32_bf16 v[82:85], v[156:159], v[234:237], v[82:85]
	s_setprio 0
	s_setprio 1
	v_mfma_f32_16x16x32_bf16 v[110:113], v[160:163], v[206:209], v[110:113]
	v_mfma_f32_16x16x32_bf16 v[106:109], v[182:185], v[206:209], v[106:109]
	v_mfma_f32_16x16x32_bf16 v[94:97], v[160:163], v[214:217], v[94:97]
	v_mfma_f32_16x16x32_bf16 v[90:93], v[182:185], v[214:217], v[90:93]
	v_mfma_f32_16x16x32_bf16 v[78:81], v[160:163], v[222:225], v[78:81]
	v_mfma_f32_16x16x32_bf16 v[74:77], v[182:185], v[222:225], v[74:77]
	v_mfma_f32_16x16x32_bf16 v[70:73], v[160:163], v[230:233], v[70:73]
	v_mfma_f32_16x16x32_bf16 v[66:69], v[182:185], v[230:233], v[66:69]
	v_mfma_f32_16x16x32_bf16 v[110:113], v[178:181], v[210:213], v[110:113]
	v_mfma_f32_16x16x32_bf16 v[106:109], v[186:189], v[210:213], v[106:109]
	v_mfma_f32_16x16x32_bf16 v[94:97], v[178:181], v[218:221], v[94:97]
	v_mfma_f32_16x16x32_bf16 v[90:93], v[186:189], v[218:221], v[90:93]
	v_mfma_f32_16x16x32_bf16 v[78:81], v[178:181], v[226:229], v[78:81]
	v_mfma_f32_16x16x32_bf16 v[74:77], v[186:189], v[226:229], v[74:77]
	v_mfma_f32_16x16x32_bf16 v[70:73], v[178:181], v[234:237], v[70:73]
	v_mfma_f32_16x16x32_bf16 v[66:69], v[186:189], v[234:237], v[66:69]
	s_setprio 0
	s_barrier
	s_add_i32 s46, s62, s72
	s_mov_b32 m0, s46
	ds_read_b128 v[206:209], v142 offset:16384
	ds_read_b128 v[210:213], v142 offset:17408
	ds_read_b128 v[214:217], v142 offset:18432
	ds_read_b128 v[218:221], v142 offset:19456
	ds_read_b128 v[222:225], v142 offset:20480
	ds_read_b128 v[226:229], v142 offset:21504
	ds_read_b128 v[230:233], v142 offset:22528
	ds_read_b128 v[234:237], v142 offset:23552
	global_load_lds_dwordx4 v166, s[60:61]
	s_add_i32 m0, s46, 0x2000
	s_add_u32 s46, s60, 0x20000
	v_lshl_add_u64 v[242:243], s[60:61], 0, v[130:131]
	s_addc_u32 s47, s61, 0
	s_add_i32 s62, s63, s72
	global_load_lds_dwordx4 v130, s[60:61]
	s_mov_b32 m0, s62
	s_nop 0
	global_load_lds_dwordx4 v166, s[46:47]
	s_add_i32 m0, s62, 0x2000
	s_nop 0
	global_load_lds_dwordx4 v130, s[46:47]
	s_mov_b32 m0, s11
	s_nop 0
	global_load_lds_dwordx4 v134, s[68:69]
	s_mov_b32 m0, s74
	s_nop 0
	global_load_lds_dwordx4 v132, s[68:69]
	s_waitcnt vmcnt(8)
	s_waitcnt lgkmcnt(0)
	s_setprio 1
	s_waitcnt lgkmcnt(0)
	v_mfma_f32_16x16x32_bf16 v[62:65], v[144:147], v[206:209], v[62:65]
	v_mfma_f32_16x16x32_bf16 v[58:61], v[152:155], v[206:209], v[58:61]
	v_mfma_f32_16x16x32_bf16 v[54:57], v[144:147], v[214:217], v[54:57]
	v_mfma_f32_16x16x32_bf16 v[50:53], v[152:155], v[214:217], v[50:53]
	s_barrier
	v_mfma_f32_16x16x32_bf16 v[38:41], v[144:147], v[222:225], v[38:41]
	v_mfma_f32_16x16x32_bf16 v[34:37], v[152:155], v[222:225], v[34:37]
	v_mfma_f32_16x16x32_bf16 v[22:25], v[144:147], v[230:233], v[22:25]
	v_mfma_f32_16x16x32_bf16 v[18:21], v[152:155], v[230:233], v[18:21]
	v_mfma_f32_16x16x32_bf16 v[62:65], v[148:151], v[210:213], v[62:65]
	v_mfma_f32_16x16x32_bf16 v[58:61], v[156:159], v[210:213], v[58:61]
	v_mfma_f32_16x16x32_bf16 v[54:57], v[148:151], v[218:221], v[54:57]
	v_mfma_f32_16x16x32_bf16 v[50:53], v[156:159], v[218:221], v[50:53]
	v_mfma_f32_16x16x32_bf16 v[38:41], v[148:151], v[226:229], v[38:41]
	v_mfma_f32_16x16x32_bf16 v[34:37], v[156:159], v[226:229], v[34:37]
	v_mfma_f32_16x16x32_bf16 v[22:25], v[148:151], v[234:237], v[22:25]
	v_mfma_f32_16x16x32_bf16 v[18:21], v[156:159], v[234:237], v[18:21]
	s_setprio 0
	s_setprio 1
	v_mfma_f32_16x16x32_bf16 v[46:49], v[160:163], v[206:209], v[46:49]
	v_mfma_f32_16x16x32_bf16 v[42:45], v[182:185], v[206:209], v[42:45]
	v_mfma_f32_16x16x32_bf16 v[30:33], v[160:163], v[214:217], v[30:33]
	v_mfma_f32_16x16x32_bf16 v[26:29], v[182:185], v[214:217], v[26:29]
	v_mfma_f32_16x16x32_bf16 v[14:17], v[160:163], v[222:225], v[14:17]
	v_mfma_f32_16x16x32_bf16 v[10:13], v[182:185], v[222:225], v[10:13]
	v_mfma_f32_16x16x32_bf16 v[6:9], v[160:163], v[230:233], v[6:9]
	v_mfma_f32_16x16x32_bf16 v[2:5], v[182:185], v[230:233], v[2:5]
	v_mfma_f32_16x16x32_bf16 v[46:49], v[178:181], v[210:213], v[46:49]
	v_mfma_f32_16x16x32_bf16 v[42:45], v[186:189], v[210:213], v[42:45]
	v_mfma_f32_16x16x32_bf16 v[30:33], v[178:181], v[218:221], v[30:33]
	v_mfma_f32_16x16x32_bf16 v[26:29], v[186:189], v[218:221], v[26:29]
	v_mfma_f32_16x16x32_bf16 v[14:17], v[178:181], v[226:229], v[14:17]
	v_mfma_f32_16x16x32_bf16 v[10:13], v[186:189], v[226:229], v[10:13]
	v_mfma_f32_16x16x32_bf16 v[6:9], v[178:181], v[234:237], v[6:9]
	v_mfma_f32_16x16x32_bf16 v[2:5], v[186:189], v[234:237], v[2:5]
	s_setprio 0
	s_barrier
	s_add_i32 s62, 0, 0x18000
	v_add_u32_e32 v143, s62, v140
	s_add_i32 s63, 0, 0x1c000
	ds_read_b128 v[144:147], v143
	ds_read_b128 v[148:151], v143 offset:1024
	ds_read_b128 v[152:155], v143 offset:2048
	ds_read_b128 v[156:159], v143 offset:3072
	v_add_u32_e32 v143, s63, v140
	ds_read_b128 v[160:163], v143
	ds_read_b128 v[178:181], v143 offset:1024
	ds_read_b128 v[182:185], v143 offset:2048
	ds_read_b128 v[186:189], v143 offset:3072
	s_add_u32 s46, s68, 0x20000
	s_addc_u32 s47, s69, 0
	s_mov_b32 m0, s75
	ds_read_b128 v[206:209], v142 offset:32768
	ds_read_b128 v[210:213], v142 offset:33792
	ds_read_b128 v[214:217], v142 offset:34816
	ds_read_b128 v[218:221], v142 offset:35840
	ds_read_b128 v[222:225], v142 offset:36864
	ds_read_b128 v[226:229], v142 offset:37888
	ds_read_b128 v[230:233], v142 offset:38912
	ds_read_b128 v[234:237], v142 offset:39936
	global_load_lds_dwordx4 v134, s[46:47]
	s_mov_b32 m0, s76
	s_nop 0
	global_load_lds_dwordx4 v132, s[46:47]
	s_waitcnt vmcnt(8)
	s_waitcnt lgkmcnt(0)
	s_setprio 1
	s_waitcnt lgkmcnt(0)
	v_mfma_f32_16x16x32_bf16 v[126:129], v[144:147], v[206:209], v[126:129]
	v_mfma_f32_16x16x32_bf16 v[122:125], v[152:155], v[206:209], v[122:125]
	v_mfma_f32_16x16x32_bf16 v[118:121], v[144:147], v[214:217], v[118:121]
	v_mfma_f32_16x16x32_bf16 v[114:117], v[152:155], v[214:217], v[114:117]
	s_barrier
	v_mfma_f32_16x16x32_bf16 v[102:105], v[144:147], v[222:225], v[102:105]
	v_mfma_f32_16x16x32_bf16 v[98:101], v[152:155], v[222:225], v[98:101]
	v_mfma_f32_16x16x32_bf16 v[86:89], v[144:147], v[230:233], v[86:89]
	v_mfma_f32_16x16x32_bf16 v[82:85], v[152:155], v[230:233], v[82:85]
	v_mfma_f32_16x16x32_bf16 v[126:129], v[148:151], v[210:213], v[126:129]
	v_mfma_f32_16x16x32_bf16 v[122:125], v[156:159], v[210:213], v[122:125]
	v_mfma_f32_16x16x32_bf16 v[118:121], v[148:151], v[218:221], v[118:121]
	v_mfma_f32_16x16x32_bf16 v[114:117], v[156:159], v[218:221], v[114:117]
	v_mfma_f32_16x16x32_bf16 v[102:105], v[148:151], v[226:229], v[102:105]
	v_mfma_f32_16x16x32_bf16 v[98:101], v[156:159], v[226:229], v[98:101]
	v_mfma_f32_16x16x32_bf16 v[86:89], v[148:151], v[234:237], v[86:89]
	v_mfma_f32_16x16x32_bf16 v[82:85], v[156:159], v[234:237], v[82:85]
	s_setprio 0
	s_setprio 1
	v_mfma_f32_16x16x32_bf16 v[110:113], v[160:163], v[206:209], v[110:113]
	v_mfma_f32_16x16x32_bf16 v[106:109], v[182:185], v[206:209], v[106:109]
	v_mfma_f32_16x16x32_bf16 v[94:97], v[160:163], v[214:217], v[94:97]
	v_mfma_f32_16x16x32_bf16 v[90:93], v[182:185], v[214:217], v[90:93]
	v_mfma_f32_16x16x32_bf16 v[78:81], v[160:163], v[222:225], v[78:81]
	v_mfma_f32_16x16x32_bf16 v[74:77], v[182:185], v[222:225], v[74:77]
	v_mfma_f32_16x16x32_bf16 v[70:73], v[160:163], v[230:233], v[70:73]
	v_mfma_f32_16x16x32_bf16 v[66:69], v[182:185], v[230:233], v[66:69]
	v_mfma_f32_16x16x32_bf16 v[110:113], v[178:181], v[210:213], v[110:113]
	v_mfma_f32_16x16x32_bf16 v[106:109], v[186:189], v[210:213], v[106:109]
	v_mfma_f32_16x16x32_bf16 v[94:97], v[178:181], v[218:221], v[94:97]
	v_mfma_f32_16x16x32_bf16 v[90:93], v[186:189], v[218:221], v[90:93]
	v_mfma_f32_16x16x32_bf16 v[78:81], v[178:181], v[226:229], v[78:81]
	v_mfma_f32_16x16x32_bf16 v[74:77], v[186:189], v[226:229], v[74:77]
	v_mfma_f32_16x16x32_bf16 v[70:73], v[178:181], v[234:237], v[70:73]
	v_mfma_f32_16x16x32_bf16 v[66:69], v[186:189], v[234:237], v[66:69]
	s_setprio 0
	s_barrier
	s_add_i32 s46, s62, s72
	s_mov_b32 m0, s46
	ds_read_b128 v[206:209], v142 offset:49152
	ds_read_b128 v[210:213], v142 offset:50176
	ds_read_b128 v[214:217], v142 offset:51200
	ds_read_b128 v[218:221], v142 offset:52224
	ds_read_b128 v[222:225], v142 offset:53248
	ds_read_b128 v[226:229], v142 offset:54272
	ds_read_b128 v[230:233], v142 offset:55296
	ds_read_b128 v[234:237], v142 offset:56320
	s_add_u32 s100, s60, 128
	s_addc_u32 s101, s61, 0
	global_load_lds_dwordx4 v166, s[100:101]
	s_add_i32 m0, s46, 0x2000
	s_add_u32 s46, s60, 0x20080
	v_lshl_add_u64 v[164:165], v[242:243], 0, s[42:43]
	s_addc_u32 s47, s61, 0
	s_add_i32 s60, s63, s72
	global_load_lds_dwordx4 v[164:165], off
	s_mov_b32 m0, s60
	s_nop 0
	global_load_lds_dwordx4 v166, s[46:47]
	s_add_i32 m0, s60, 0x2000
	s_nop 0
	global_load_lds_dwordx4 v130, s[46:47]
	s_mov_b32 m0, s77
	s_nop 0
	s_add_u32 s100, s68, 128
	s_addc_u32 s101, s69, 0
	global_load_lds_dwordx4 v134, s[100:101]
	s_mov_b32 m0, s78
	s_nop 0
	s_add_u32 s100, s68, 128
	s_addc_u32 s101, s69, 0
	global_load_lds_dwordx4 v132, s[100:101]
	s_waitcnt vmcnt(8)
	s_waitcnt lgkmcnt(0)
	s_setprio 1
	s_waitcnt lgkmcnt(0)
	v_mfma_f32_16x16x32_bf16 v[62:65], v[144:147], v[206:209], v[62:65]
	v_mfma_f32_16x16x32_bf16 v[58:61], v[152:155], v[206:209], v[58:61]
	v_mfma_f32_16x16x32_bf16 v[54:57], v[144:147], v[214:217], v[54:57]
	v_mfma_f32_16x16x32_bf16 v[50:53], v[152:155], v[214:217], v[50:53]
	s_barrier
	v_mfma_f32_16x16x32_bf16 v[38:41], v[144:147], v[222:225], v[38:41]
	v_mfma_f32_16x16x32_bf16 v[34:37], v[152:155], v[222:225], v[34:37]
	v_mfma_f32_16x16x32_bf16 v[22:25], v[144:147], v[230:233], v[22:25]
	v_mfma_f32_16x16x32_bf16 v[18:21], v[152:155], v[230:233], v[18:21]
	v_mfma_f32_16x16x32_bf16 v[62:65], v[148:151], v[210:213], v[62:65]
	v_mfma_f32_16x16x32_bf16 v[58:61], v[156:159], v[210:213], v[58:61]
	v_mfma_f32_16x16x32_bf16 v[54:57], v[148:151], v[218:221], v[54:57]
	v_mfma_f32_16x16x32_bf16 v[50:53], v[156:159], v[218:221], v[50:53]
	v_mfma_f32_16x16x32_bf16 v[38:41], v[148:151], v[226:229], v[38:41]
	v_mfma_f32_16x16x32_bf16 v[34:37], v[156:159], v[226:229], v[34:37]
	v_mfma_f32_16x16x32_bf16 v[22:25], v[148:151], v[234:237], v[22:25]
	v_mfma_f32_16x16x32_bf16 v[18:21], v[156:159], v[234:237], v[18:21]
	s_setprio 0
	s_setprio 1
	v_mfma_f32_16x16x32_bf16 v[46:49], v[160:163], v[206:209], v[46:49]
	v_mfma_f32_16x16x32_bf16 v[42:45], v[182:185], v[206:209], v[42:45]
	v_mfma_f32_16x16x32_bf16 v[30:33], v[160:163], v[214:217], v[30:33]
	v_mfma_f32_16x16x32_bf16 v[26:29], v[182:185], v[214:217], v[26:29]
	v_mfma_f32_16x16x32_bf16 v[14:17], v[160:163], v[222:225], v[14:17]
	v_mfma_f32_16x16x32_bf16 v[10:13], v[182:185], v[222:225], v[10:13]
	v_mfma_f32_16x16x32_bf16 v[6:9], v[160:163], v[230:233], v[6:9]
	v_mfma_f32_16x16x32_bf16 v[2:5], v[182:185], v[230:233], v[2:5]
	v_mfma_f32_16x16x32_bf16 v[46:49], v[178:181], v[210:213], v[46:49]
	v_mfma_f32_16x16x32_bf16 v[42:45], v[186:189], v[210:213], v[42:45]
	v_mfma_f32_16x16x32_bf16 v[30:33], v[178:181], v[218:221], v[30:33]
	v_mfma_f32_16x16x32_bf16 v[26:29], v[186:189], v[218:221], v[26:29]
	v_mfma_f32_16x16x32_bf16 v[14:17], v[178:181], v[226:229], v[14:17]
	v_mfma_f32_16x16x32_bf16 v[10:13], v[186:189], v[226:229], v[10:13]
	v_mfma_f32_16x16x32_bf16 v[6:9], v[178:181], v[234:237], v[6:9]
	v_mfma_f32_16x16x32_bf16 v[2:5], v[186:189], v[234:237], v[2:5]
	s_setprio 0
	s_barrier
	s_add_i32 s84, s84, 2
	s_add_u32 s66, s66, 0x100
	s_addc_u32 s67, s67, 0
	s_add_u32 s82, s82, 0x100
	s_addc_u32 s83, s83, 0
	s_cmp_gt_u32 s84, 5
	s_cbranch_scc0 .LBB0_426
	s_and_b64 vcc, exec, s[12:13]
	s_cbranch_vccz .LBB0_429
	s_barrier

.LBB0_442:
	s_add_u32 s62, s18, s72
	s_addc_u32 s63, s19, 0
	s_add_u32 s73, s62, 0x100
	s_addc_u32 s74, s63, 0
	s_and_b64 s[46:47], s[60:61], exec
	s_cselect_b32 s75, s23, s74
	s_cselect_b32 s74, s92, s73
	s_add_u32 s46, s16, s72
	s_addc_u32 s47, s17, 0
	s_add_u32 s72, s46, 0x100
	s_addc_u32 s73, s47, 0
	s_add_i32 s48, 0, 0x10000
	s_and_b64 s[46:47], s[60:61], exec
	s_cselect_b32 s77, s21, s73
	s_cselect_b32 s76, s93, s72
	s_add_i32 s46, 0, 0x14000
	s_add_u32 s80, s62, 0x10080
	s_addc_u32 s81, s63, 0
	s_add_i32 s63, s48, s84
	s_add_i32 m0, s13, 0xc000
	s_add_i32 s49, s13, 0xe000
	s_add_i32 vcc_lo, s63, 0x2000
	v_add_u32_e32 v139, s48, v136
	s_add_u32 s78, s76, 0x10000
	ds_read_b128 v[140:143], v139
	ds_read_b128 v[144:147], v139 offset:1024
	ds_read_b128 v[148:151], v139 offset:2048
	ds_read_b128 v[152:155], v139 offset:3072
	v_add_u32_e32 v139, s46, v136
	s_addc_u32 s79, s77, 0
	s_add_i32 vcc_hi, s46, s84
	ds_read_b128 v[156:159], v139
	ds_read_b128 v[160:163], v139 offset:1024
	ds_read_b128 v[178:181], v139 offset:2048
	ds_read_b128 v[182:185], v139 offset:3072
	s_add_i32 s62, vcc_hi, 0x2000
	s_add_i32 s97, 0, 0x18000
	s_add_i32 s96, 0, 0x1c000
	s_add_u32 s72, s74, 0x10000
	s_addc_u32 s73, s75, 0
	s_add_i32 s95, s97, s84
	s_add_i32 s94, s95, 0x2000
	s_add_u32 s60, s76, 0x10080
	s_addc_u32 s61, s77, 0
	s_add_i32 s47, s96, s84
	s_add_i32 s46, s47, 0x2000
	ds_read_b128 v[186:189], v138
	ds_read_b128 v[206:209], v138 offset:1024
	ds_read_b128 v[210:213], v138 offset:2048
	ds_read_b128 v[214:217], v138 offset:3072
	ds_read_b128 v[218:221], v138 offset:4096
	ds_read_b128 v[222:225], v138 offset:5120
	ds_read_b128 v[226:229], v138 offset:6144
	ds_read_b128 v[230:233], v138 offset:7168
	global_load_lds_dwordx4 v134, s[80:81]
	s_mov_b32 m0, s49
	s_nop 0
	global_load_lds_dwordx4 v132, s[80:81]
	s_waitcnt vmcnt(8)
	s_waitcnt lgkmcnt(0)
	s_setprio 1
	s_waitcnt lgkmcnt(0)
	v_mfma_f32_16x16x32_bf16 v[126:129], v[140:143], v[186:189], v[126:129]
	v_mfma_f32_16x16x32_bf16 v[122:125], v[148:151], v[186:189], v[122:125]
	v_mfma_f32_16x16x32_bf16 v[118:121], v[140:143], v[210:213], v[118:121]
	v_mfma_f32_16x16x32_bf16 v[114:117], v[148:151], v[210:213], v[114:117]
	s_barrier
	v_mfma_f32_16x16x32_bf16 v[102:105], v[140:143], v[218:221], v[102:105]
	v_mfma_f32_16x16x32_bf16 v[98:101], v[148:151], v[218:221], v[98:101]
	v_mfma_f32_16x16x32_bf16 v[86:89], v[140:143], v[226:229], v[86:89]
	v_mfma_f32_16x16x32_bf16 v[82:85], v[148:151], v[226:229], v[82:85]
	v_mfma_f32_16x16x32_bf16 v[126:129], v[144:147], v[206:209], v[126:129]
	v_mfma_f32_16x16x32_bf16 v[122:125], v[152:155], v[206:209], v[122:125]
	v_mfma_f32_16x16x32_bf16 v[118:121], v[144:147], v[214:217], v[118:121]
	v_mfma_f32_16x16x32_bf16 v[114:117], v[152:155], v[214:217], v[114:117]
	v_mfma_f32_16x16x32_bf16 v[102:105], v[144:147], v[222:225], v[102:105]
	v_mfma_f32_16x16x32_bf16 v[98:101], v[152:155], v[222:225], v[98:101]
	v_mfma_f32_16x16x32_bf16 v[86:89], v[144:147], v[230:233], v[86:89]
	v_mfma_f32_16x16x32_bf16 v[82:85], v[152:155], v[230:233], v[82:85]
	s_setprio 0
	s_setprio 1
	v_mfma_f32_16x16x32_bf16 v[110:113], v[156:159], v[186:189], v[110:113]
	v_mfma_f32_16x16x32_bf16 v[106:109], v[178:181], v[186:189], v[106:109]
	v_mfma_f32_16x16x32_bf16 v[94:97], v[156:159], v[210:213], v[94:97]
	v_mfma_f32_16x16x32_bf16 v[90:93], v[178:181], v[210:213], v[90:93]
	v_mfma_f32_16x16x32_bf16 v[78:81], v[156:159], v[218:221], v[78:81]
	v_mfma_f32_16x16x32_bf16 v[74:77], v[178:181], v[218:221], v[74:77]
	v_mfma_f32_16x16x32_bf16 v[70:73], v[156:159], v[226:229], v[70:73]
	v_mfma_f32_16x16x32_bf16 v[66:69], v[178:181], v[226:229], v[66:69]
	v_mfma_f32_16x16x32_bf16 v[110:113], v[160:163], v[206:209], v[110:113]
	v_mfma_f32_16x16x32_bf16 v[106:109], v[182:185], v[206:209], v[106:109]
	v_mfma_f32_16x16x32_bf16 v[94:97], v[160:163], v[214:217], v[94:97]
	v_mfma_f32_16x16x32_bf16 v[90:93], v[182:185], v[214:217], v[90:93]
	v_mfma_f32_16x16x32_bf16 v[78:81], v[160:163], v[222:225], v[78:81]
	v_mfma_f32_16x16x32_bf16 v[74:77], v[182:185], v[222:225], v[74:77]
	v_mfma_f32_16x16x32_bf16 v[70:73], v[160:163], v[230:233], v[70:73]
	v_mfma_f32_16x16x32_bf16 v[66:69], v[182:185], v[230:233], v[66:69]
	s_setprio 0
	s_barrier
	s_mov_b32 m0, s63
	ds_read_b128 v[186:189], v138 offset:16384
	ds_read_b128 v[206:209], v138 offset:17408
	ds_read_b128 v[210:213], v138 offset:18432
	ds_read_b128 v[214:217], v138 offset:19456
	ds_read_b128 v[218:221], v138 offset:20480
	ds_read_b128 v[222:225], v138 offset:21504
	ds_read_b128 v[226:229], v138 offset:22528
	ds_read_b128 v[230:233], v138 offset:23552
	global_load_lds_dwordx4 v166, s[76:77]
	s_mov_b32 m0, vcc_lo
	s_nop 0
	global_load_lds_dwordx4 v130, s[76:77]
	s_mov_b32 m0, vcc_hi
	s_nop 0
	global_load_lds_dwordx4 v166, s[78:79]
	s_mov_b32 m0, s62
	s_nop 0
	global_load_lds_dwordx4 v130, s[78:79]
	s_mov_b32 m0, s13
	s_nop 0
	global_load_lds_dwordx4 v134, s[74:75]
	s_mov_b32 m0, s86
	s_nop 0
	global_load_lds_dwordx4 v132, s[74:75]
	s_waitcnt vmcnt(8)
	s_waitcnt lgkmcnt(0)
	s_setprio 1
	s_waitcnt lgkmcnt(0)
	v_mfma_f32_16x16x32_bf16 v[62:65], v[140:143], v[186:189], v[62:65]
	v_mfma_f32_16x16x32_bf16 v[58:61], v[148:151], v[186:189], v[58:61]
	v_mfma_f32_16x16x32_bf16 v[54:57], v[140:143], v[210:213], v[54:57]
	v_mfma_f32_16x16x32_bf16 v[50:53], v[148:151], v[210:213], v[50:53]
	s_barrier
	v_mfma_f32_16x16x32_bf16 v[38:41], v[140:143], v[218:221], v[38:41]
	v_mfma_f32_16x16x32_bf16 v[34:37], v[148:151], v[218:221], v[34:37]
	v_mfma_f32_16x16x32_bf16 v[22:25], v[140:143], v[226:229], v[22:25]
	v_mfma_f32_16x16x32_bf16 v[18:21], v[148:151], v[226:229], v[18:21]
	v_mfma_f32_16x16x32_bf16 v[62:65], v[144:147], v[206:209], v[62:65]
	v_mfma_f32_16x16x32_bf16 v[58:61], v[152:155], v[206:209], v[58:61]
	v_mfma_f32_16x16x32_bf16 v[54:57], v[144:147], v[214:217], v[54:57]
	v_mfma_f32_16x16x32_bf16 v[50:53], v[152:155], v[214:217], v[50:53]
	v_mfma_f32_16x16x32_bf16 v[38:41], v[144:147], v[222:225], v[38:41]
	v_mfma_f32_16x16x32_bf16 v[34:37], v[152:155], v[222:225], v[34:37]
	v_mfma_f32_16x16x32_bf16 v[22:25], v[144:147], v[230:233], v[22:25]
	v_mfma_f32_16x16x32_bf16 v[18:21], v[152:155], v[230:233], v[18:21]
	s_setprio 0
	s_setprio 1
	v_mfma_f32_16x16x32_bf16 v[46:49], v[156:159], v[186:189], v[46:49]
	v_mfma_f32_16x16x32_bf16 v[42:45], v[178:181], v[186:189], v[42:45]
	v_mfma_f32_16x16x32_bf16 v[30:33], v[156:159], v[210:213], v[30:33]
	v_mfma_f32_16x16x32_bf16 v[26:29], v[178:181], v[210:213], v[26:29]
	v_mfma_f32_16x16x32_bf16 v[14:17], v[156:159], v[218:221], v[14:17]
	v_mfma_f32_16x16x32_bf16 v[10:13], v[178:181], v[218:221], v[10:13]
	v_mfma_f32_16x16x32_bf16 v[6:9], v[156:159], v[226:229], v[6:9]
	v_mfma_f32_16x16x32_bf16 v[2:5], v[178:181], v[226:229], v[2:5]
	v_mfma_f32_16x16x32_bf16 v[46:49], v[160:163], v[206:209], v[46:49]
	v_mfma_f32_16x16x32_bf16 v[42:45], v[182:185], v[206:209], v[42:45]
	v_mfma_f32_16x16x32_bf16 v[30:33], v[160:163], v[214:217], v[30:33]
	v_mfma_f32_16x16x32_bf16 v[26:29], v[182:185], v[214:217], v[26:29]
	v_mfma_f32_16x16x32_bf16 v[14:17], v[160:163], v[222:225], v[14:17]
	v_mfma_f32_16x16x32_bf16 v[10:13], v[182:185], v[222:225], v[10:13]
	v_mfma_f32_16x16x32_bf16 v[6:9], v[160:163], v[230:233], v[6:9]
	v_mfma_f32_16x16x32_bf16 v[2:5], v[182:185], v[230:233], v[2:5]
	s_setprio 0
	s_barrier
	v_add_u32_e32 v139, s97, v136
	ds_read_b128 v[140:143], v139
	ds_read_b128 v[144:147], v139 offset:1024
	ds_read_b128 v[148:151], v139 offset:2048
	ds_read_b128 v[152:155], v139 offset:3072
	v_add_u32_e32 v139, s96, v136
	ds_read_b128 v[156:159], v139
	ds_read_b128 v[160:163], v139 offset:1024
	ds_read_b128 v[178:181], v139 offset:2048
	ds_read_b128 v[182:185], v139 offset:3072
	s_mov_b32 m0, s87
	ds_read_b128 v[186:189], v138 offset:32768
	ds_read_b128 v[206:209], v138 offset:33792
	ds_read_b128 v[210:213], v138 offset:34816
	ds_read_b128 v[214:217], v138 offset:35840
	ds_read_b128 v[218:221], v138 offset:36864
	ds_read_b128 v[222:225], v138 offset:37888
	ds_read_b128 v[226:229], v138 offset:38912
	ds_read_b128 v[230:233], v138 offset:39936
	global_load_lds_dwordx4 v134, s[72:73]
	s_mov_b32 m0, s88
	s_nop 0
	global_load_lds_dwordx4 v132, s[72:73]
	s_waitcnt vmcnt(8)
	s_waitcnt lgkmcnt(0)
	s_setprio 1
	s_waitcnt lgkmcnt(0)
	v_mfma_f32_16x16x32_bf16 v[126:129], v[140:143], v[186:189], v[126:129]
	v_mfma_f32_16x16x32_bf16 v[122:125], v[148:151], v[186:189], v[122:125]
	v_mfma_f32_16x16x32_bf16 v[118:121], v[140:143], v[210:213], v[118:121]
	v_mfma_f32_16x16x32_bf16 v[114:117], v[148:151], v[210:213], v[114:117]
	s_barrier
	v_mfma_f32_16x16x32_bf16 v[102:105], v[140:143], v[218:221], v[102:105]
	v_mfma_f32_16x16x32_bf16 v[98:101], v[148:151], v[218:221], v[98:101]
	v_mfma_f32_16x16x32_bf16 v[86:89], v[140:143], v[226:229], v[86:89]
	v_mfma_f32_16x16x32_bf16 v[82:85], v[148:151], v[226:229], v[82:85]
	v_mfma_f32_16x16x32_bf16 v[126:129], v[144:147], v[206:209], v[126:129]
	v_mfma_f32_16x16x32_bf16 v[122:125], v[152:155], v[206:209], v[122:125]
	v_mfma_f32_16x16x32_bf16 v[118:121], v[144:147], v[214:217], v[118:121]
	v_mfma_f32_16x16x32_bf16 v[114:117], v[152:155], v[214:217], v[114:117]
	v_mfma_f32_16x16x32_bf16 v[102:105], v[144:147], v[222:225], v[102:105]
	v_mfma_f32_16x16x32_bf16 v[98:101], v[152:155], v[222:225], v[98:101]
	v_mfma_f32_16x16x32_bf16 v[86:89], v[144:147], v[230:233], v[86:89]
	v_mfma_f32_16x16x32_bf16 v[82:85], v[152:155], v[230:233], v[82:85]
	s_setprio 0
	s_setprio 1
	v_mfma_f32_16x16x32_bf16 v[110:113], v[156:159], v[186:189], v[110:113]
	v_mfma_f32_16x16x32_bf16 v[106:109], v[178:181], v[186:189], v[106:109]
	v_mfma_f32_16x16x32_bf16 v[94:97], v[156:159], v[210:213], v[94:97]
	v_mfma_f32_16x16x32_bf16 v[90:93], v[178:181], v[210:213], v[90:93]
	v_mfma_f32_16x16x32_bf16 v[78:81], v[156:159], v[218:221], v[78:81]
	v_mfma_f32_16x16x32_bf16 v[74:77], v[178:181], v[218:221], v[74:77]
	v_mfma_f32_16x16x32_bf16 v[70:73], v[156:159], v[226:229], v[70:73]
	v_mfma_f32_16x16x32_bf16 v[66:69], v[178:181], v[226:229], v[66:69]
	v_mfma_f32_16x16x32_bf16 v[110:113], v[160:163], v[206:209], v[110:113]
	v_mfma_f32_16x16x32_bf16 v[106:109], v[182:185], v[206:209], v[106:109]
	v_mfma_f32_16x16x32_bf16 v[94:97], v[160:163], v[214:217], v[94:97]
	v_mfma_f32_16x16x32_bf16 v[90:93], v[182:185], v[214:217], v[90:93]
	v_mfma_f32_16x16x32_bf16 v[78:81], v[160:163], v[222:225], v[78:81]
	v_mfma_f32_16x16x32_bf16 v[74:77], v[182:185], v[222:225], v[74:77]
	v_mfma_f32_16x16x32_bf16 v[70:73], v[160:163], v[230:233], v[70:73]
	v_mfma_f32_16x16x32_bf16 v[66:69], v[182:185], v[230:233], v[66:69]
	s_setprio 0
	s_barrier
	s_mov_b32 m0, s95
	ds_read_b128 v[186:189], v138 offset:49152
	ds_read_b128 v[206:209], v138 offset:50176
	ds_read_b128 v[210:213], v138 offset:51200
	ds_read_b128 v[214:217], v138 offset:52224
	ds_read_b128 v[218:221], v138 offset:53248
	ds_read_b128 v[222:225], v138 offset:54272
	ds_read_b128 v[226:229], v138 offset:55296
	ds_read_b128 v[230:233], v138 offset:56320
	s_add_u32 s100, s76, 128
	s_addc_u32 s101, s77, 0
	global_load_lds_dwordx4 v166, s[100:101]
	s_mov_b32 m0, s94
	s_nop 0
	s_add_u32 s100, s76, 128
	s_addc_u32 s101, s77, 0
	global_load_lds_dwordx4 v130, s[100:101]
	s_mov_b32 m0, s47
	s_nop 0
	global_load_lds_dwordx4 v166, s[60:61]
	s_mov_b32 m0, s46
	s_nop 0
	global_load_lds_dwordx4 v130, s[60:61]
	s_mov_b32 m0, s89
	s_nop 0
	s_add_u32 s100, s74, 128
	s_addc_u32 s101, s75, 0
	global_load_lds_dwordx4 v134, s[100:101]
	s_mov_b32 m0, s90
	s_nop 0
	s_add_u32 s100, s74, 128
	s_addc_u32 s101, s75, 0
	global_load_lds_dwordx4 v132, s[100:101]
	s_waitcnt vmcnt(8)
	s_waitcnt lgkmcnt(0)
	s_setprio 1
	s_waitcnt lgkmcnt(0)
	v_mfma_f32_16x16x32_bf16 v[62:65], v[140:143], v[186:189], v[62:65]
	v_mfma_f32_16x16x32_bf16 v[58:61], v[148:151], v[186:189], v[58:61]
	v_mfma_f32_16x16x32_bf16 v[54:57], v[140:143], v[210:213], v[54:57]
	v_mfma_f32_16x16x32_bf16 v[50:53], v[148:151], v[210:213], v[50:53]
	s_barrier
	v_mfma_f32_16x16x32_bf16 v[38:41], v[140:143], v[218:221], v[38:41]
	v_mfma_f32_16x16x32_bf16 v[34:37], v[148:151], v[218:221], v[34:37]
	v_mfma_f32_16x16x32_bf16 v[22:25], v[140:143], v[226:229], v[22:25]
	v_mfma_f32_16x16x32_bf16 v[18:21], v[148:151], v[226:229], v[18:21]
	v_mfma_f32_16x16x32_bf16 v[62:65], v[144:147], v[206:209], v[62:65]
	v_mfma_f32_16x16x32_bf16 v[58:61], v[152:155], v[206:209], v[58:61]
	v_mfma_f32_16x16x32_bf16 v[54:57], v[144:147], v[214:217], v[54:57]
	v_mfma_f32_16x16x32_bf16 v[50:53], v[152:155], v[214:217], v[50:53]
	v_mfma_f32_16x16x32_bf16 v[38:41], v[144:147], v[222:225], v[38:41]
	v_mfma_f32_16x16x32_bf16 v[34:37], v[152:155], v[222:225], v[34:37]
	v_mfma_f32_16x16x32_bf16 v[22:25], v[144:147], v[230:233], v[22:25]
	v_mfma_f32_16x16x32_bf16 v[18:21], v[152:155], v[230:233], v[18:21]
	s_setprio 0
	s_setprio 1
	v_mfma_f32_16x16x32_bf16 v[46:49], v[156:159], v[186:189], v[46:49]
	v_mfma_f32_16x16x32_bf16 v[42:45], v[178:181], v[186:189], v[42:45]
	v_mfma_f32_16x16x32_bf16 v[30:33], v[156:159], v[210:213], v[30:33]
	v_mfma_f32_16x16x32_bf16 v[26:29], v[178:181], v[210:213], v[26:29]
	v_mfma_f32_16x16x32_bf16 v[14:17], v[156:159], v[218:221], v[14:17]
	v_mfma_f32_16x16x32_bf16 v[10:13], v[178:181], v[218:221], v[10:13]
	v_mfma_f32_16x16x32_bf16 v[6:9], v[156:159], v[226:229], v[6:9]
	v_mfma_f32_16x16x32_bf16 v[2:5], v[178:181], v[226:229], v[2:5]
	v_mfma_f32_16x16x32_bf16 v[46:49], v[160:163], v[206:209], v[46:49]
	v_mfma_f32_16x16x32_bf16 v[42:45], v[182:185], v[206:209], v[42:45]
	v_mfma_f32_16x16x32_bf16 v[30:33], v[160:163], v[214:217], v[30:33]
	v_mfma_f32_16x16x32_bf16 v[26:29], v[182:185], v[214:217], v[26:29]
	v_mfma_f32_16x16x32_bf16 v[14:17], v[160:163], v[222:225], v[14:17]
	v_mfma_f32_16x16x32_bf16 v[10:13], v[182:185], v[222:225], v[10:13]
	v_mfma_f32_16x16x32_bf16 v[6:9], v[160:163], v[230:233], v[6:9]
	v_mfma_f32_16x16x32_bf16 v[2:5], v[182:185], v[230:233], v[2:5]
	s_setprio 0
	s_barrier
	s_movk_i32 s72, 0x100
	s_andn2_b64 vcc, exec, s[70:71]
	s_mov_b64 s[60:61], -1
	s_mov_b64 s[70:71], 0
	s_cbranch_vccz .LBB0_442
	s_and_b64 vcc, exec, s[10:11]
	s_cbranch_vccz .LBB0_445
	s_barrier

.LBB0_795:
	s_add_u32 s46, s68, 0xfff80080
	s_addc_u32 s47, s69, -1
	s_add_i32 s48, 0, 0x10000
	s_cmp_eq_u32 s87, 28
	s_cselect_b32 s71, s19, s47
	s_cselect_b32 s70, s83, s46
	s_cselect_b32 s61, s17, s86
	s_cselect_b32 s60, s84, s85
	s_add_i32 s49, 0, 0x14000
	v_add_u32_e32 v156, s48, v1
	v_add_u32_e32 v164, s49, v1
	ds_read_b128 v[130:133], v156
	ds_read_b128 v[134:137], v156 offset:1024
	ds_read_b128 v[150:153], v156 offset:2048
	ds_read_b128 v[156:159], v156 offset:3072
	ds_read_b128 v[160:163], v164
	ds_read_b128 v[178:181], v164 offset:1024
	ds_read_b128 v[182:185], v164 offset:2048
	ds_read_b128 v[186:189], v164 offset:3072
	s_add_i32 m0, s67, 0xc000
	ds_read_b128 v[206:209], v155
	ds_read_b128 v[210:213], v155 offset:1024
	ds_read_b128 v[214:217], v155 offset:2048
	ds_read_b128 v[218:221], v155 offset:3072
	ds_read_b128 v[222:225], v155 offset:4096
	ds_read_b128 v[226:229], v155 offset:5120
	ds_read_b128 v[230:233], v155 offset:6144
	ds_read_b128 v[234:237], v155 offset:7168
	global_load_lds_dwordx4 v146, s[68:69]
	s_add_i32 m0, s67, 0xe000
	s_nop 0
	global_load_lds_dwordx4 v148, s[68:69]
	s_waitcnt vmcnt(8)
	s_waitcnt lgkmcnt(0)
	s_setprio 1
	s_waitcnt lgkmcnt(0)
	v_mfma_f32_16x16x32_bf16 v[126:129], v[130:133], v[206:209], v[126:129]
	v_mfma_f32_16x16x32_bf16 v[122:125], v[150:153], v[206:209], v[122:125]
	v_mfma_f32_16x16x32_bf16 v[118:121], v[130:133], v[214:217], v[118:121]
	v_mfma_f32_16x16x32_bf16 v[114:117], v[150:153], v[214:217], v[114:117]
	s_barrier
	v_mfma_f32_16x16x32_bf16 v[110:113], v[130:133], v[222:225], v[110:113]
	v_mfma_f32_16x16x32_bf16 v[106:109], v[150:153], v[222:225], v[106:109]
	v_mfma_f32_16x16x32_bf16 v[102:105], v[130:133], v[230:233], v[102:105]
	v_mfma_f32_16x16x32_bf16 v[98:101], v[150:153], v[230:233], v[98:101]
	v_mfma_f32_16x16x32_bf16 v[126:129], v[134:137], v[210:213], v[126:129]
	v_mfma_f32_16x16x32_bf16 v[122:125], v[156:159], v[210:213], v[122:125]
	v_mfma_f32_16x16x32_bf16 v[118:121], v[134:137], v[218:221], v[118:121]
	v_mfma_f32_16x16x32_bf16 v[114:117], v[156:159], v[218:221], v[114:117]
	v_mfma_f32_16x16x32_bf16 v[110:113], v[134:137], v[226:229], v[110:113]
	v_mfma_f32_16x16x32_bf16 v[106:109], v[156:159], v[226:229], v[106:109]
	v_mfma_f32_16x16x32_bf16 v[102:105], v[134:137], v[234:237], v[102:105]
	v_mfma_f32_16x16x32_bf16 v[98:101], v[156:159], v[234:237], v[98:101]
	s_setprio 0
	s_setprio 1
	v_mfma_f32_16x16x32_bf16 v[66:69], v[160:163], v[206:209], v[66:69]
	v_mfma_f32_16x16x32_bf16 v[58:61], v[182:185], v[206:209], v[58:61]
	v_mfma_f32_16x16x32_bf16 v[54:57], v[160:163], v[214:217], v[54:57]
	v_mfma_f32_16x16x32_bf16 v[50:53], v[182:185], v[214:217], v[50:53]
	v_mfma_f32_16x16x32_bf16 v[46:49], v[160:163], v[222:225], v[46:49]
	v_mfma_f32_16x16x32_bf16 v[42:45], v[182:185], v[222:225], v[42:45]
	v_mfma_f32_16x16x32_bf16 v[38:41], v[160:163], v[230:233], v[38:41]
	v_mfma_f32_16x16x32_bf16 v[34:37], v[182:185], v[230:233], v[34:37]
	v_mfma_f32_16x16x32_bf16 v[66:69], v[178:181], v[210:213], v[66:69]
	v_mfma_f32_16x16x32_bf16 v[58:61], v[186:189], v[210:213], v[58:61]
	v_mfma_f32_16x16x32_bf16 v[54:57], v[178:181], v[218:221], v[54:57]
	v_mfma_f32_16x16x32_bf16 v[50:53], v[186:189], v[218:221], v[50:53]
	v_mfma_f32_16x16x32_bf16 v[46:49], v[178:181], v[226:229], v[46:49]
	v_mfma_f32_16x16x32_bf16 v[42:45], v[186:189], v[226:229], v[42:45]
	v_mfma_f32_16x16x32_bf16 v[38:41], v[178:181], v[234:237], v[38:41]
	v_mfma_f32_16x16x32_bf16 v[34:37], v[186:189], v[234:237], v[34:37]
	s_setprio 0
	s_barrier
	s_add_i32 s46, s48, s77
	s_mov_b32 m0, s46
	ds_read_b128 v[206:209], v155 offset:16384
	ds_read_b128 v[210:213], v155 offset:17408
	ds_read_b128 v[214:217], v155 offset:18432
	ds_read_b128 v[218:221], v155 offset:19456
	ds_read_b128 v[222:225], v155 offset:20480
	ds_read_b128 v[226:229], v155 offset:21504
	ds_read_b128 v[230:233], v155 offset:22528
	ds_read_b128 v[234:237], v155 offset:23552
	global_load_lds_dwordx4 v166, s[60:61]
	s_add_i32 m0, s46, 0x2000
	s_add_u32 s46, s60, 0x80000
	s_addc_u32 s47, s61, 0
	s_add_i32 s48, s49, s77
	global_load_lds_dwordx4 v142, s[60:61]
	s_mov_b32 m0, s48
	s_nop 0
	global_load_lds_dwordx4 v166, s[46:47]
	s_add_i32 m0, s48, 0x2000
	s_nop 0
	global_load_lds_dwordx4 v142, s[46:47]
	s_mov_b32 m0, s67
	s_nop 0
	global_load_lds_dwordx4 v138, s[70:71]
	s_mov_b32 m0, s78
	s_nop 0
	global_load_lds_dwordx4 v140, s[70:71]
	s_waitcnt vmcnt(8)
	s_waitcnt lgkmcnt(0)
	s_setprio 1
	s_waitcnt lgkmcnt(0)
	v_mfma_f32_16x16x32_bf16 v[94:97], v[130:133], v[206:209], v[94:97]
	v_mfma_f32_16x16x32_bf16 v[90:93], v[150:153], v[206:209], v[90:93]
	v_mfma_f32_16x16x32_bf16 v[86:89], v[130:133], v[214:217], v[86:89]
	v_mfma_f32_16x16x32_bf16 v[82:85], v[150:153], v[214:217], v[82:85]
	s_barrier
	v_mfma_f32_16x16x32_bf16 v[78:81], v[130:133], v[222:225], v[78:81]
	v_mfma_f32_16x16x32_bf16 v[74:77], v[150:153], v[222:225], v[74:77]
	v_mfma_f32_16x16x32_bf16 v[70:73], v[130:133], v[230:233], v[70:73]
	v_mfma_f32_16x16x32_bf16 v[62:65], v[150:153], v[230:233], v[62:65]
	v_mfma_f32_16x16x32_bf16 v[94:97], v[134:137], v[210:213], v[94:97]
	v_mfma_f32_16x16x32_bf16 v[90:93], v[156:159], v[210:213], v[90:93]
	v_mfma_f32_16x16x32_bf16 v[86:89], v[134:137], v[218:221], v[86:89]
	v_mfma_f32_16x16x32_bf16 v[82:85], v[156:159], v[218:221], v[82:85]
	v_mfma_f32_16x16x32_bf16 v[78:81], v[134:137], v[226:229], v[78:81]
	v_mfma_f32_16x16x32_bf16 v[74:77], v[156:159], v[226:229], v[74:77]
	v_mfma_f32_16x16x32_bf16 v[70:73], v[134:137], v[234:237], v[70:73]
	v_mfma_f32_16x16x32_bf16 v[62:65], v[156:159], v[234:237], v[62:65]
	s_setprio 0
	s_setprio 1
	v_mfma_f32_16x16x32_bf16 v[30:33], v[160:163], v[206:209], v[30:33]
	v_mfma_f32_16x16x32_bf16 v[26:29], v[182:185], v[206:209], v[26:29]
	v_mfma_f32_16x16x32_bf16 v[22:25], v[160:163], v[214:217], v[22:25]
	v_mfma_f32_16x16x32_bf16 v[18:21], v[182:185], v[214:217], v[18:21]
	v_mfma_f32_16x16x32_bf16 v[14:17], v[160:163], v[222:225], v[14:17]
	v_mfma_f32_16x16x32_bf16 v[10:13], v[182:185], v[222:225], v[10:13]
	v_mfma_f32_16x16x32_bf16 v[6:9], v[160:163], v[230:233], v[6:9]
	v_mfma_f32_16x16x32_bf16 v[2:5], v[182:185], v[230:233], v[2:5]
	v_mfma_f32_16x16x32_bf16 v[30:33], v[178:181], v[210:213], v[30:33]
	v_mfma_f32_16x16x32_bf16 v[26:29], v[186:189], v[210:213], v[26:29]
	v_mfma_f32_16x16x32_bf16 v[22:25], v[178:181], v[218:221], v[22:25]
	v_mfma_f32_16x16x32_bf16 v[18:21], v[186:189], v[218:221], v[18:21]
	v_mfma_f32_16x16x32_bf16 v[14:17], v[178:181], v[226:229], v[14:17]
	v_mfma_f32_16x16x32_bf16 v[10:13], v[186:189], v[226:229], v[10:13]
	v_mfma_f32_16x16x32_bf16 v[6:9], v[178:181], v[234:237], v[6:9]
	v_mfma_f32_16x16x32_bf16 v[2:5], v[186:189], v[234:237], v[2:5]
	s_setprio 0
	s_barrier
	s_add_i32 s48, 0, 0x18000
	s_add_i32 s49, 0, 0x1c000
	v_add_u32_e32 v156, s48, v1
	v_add_u32_e32 v186, s49, v1
	ds_read_b128 v[130:133], v156
	ds_read_b128 v[134:137], v156 offset:1024
	ds_read_b128 v[150:153], v156 offset:2048
	ds_read_b128 v[156:159], v156 offset:3072
	ds_read_b128 v[160:163], v186
	ds_read_b128 v[178:181], v186 offset:1024
	ds_read_b128 v[182:185], v186 offset:2048
	ds_read_b128 v[186:189], v186 offset:3072
	s_add_u32 s46, s70, 0x80000
	s_addc_u32 s47, s71, 0
	s_mov_b32 m0, s79
	ds_read_b128 v[206:209], v155 offset:32768
	ds_read_b128 v[210:213], v155 offset:33792
	ds_read_b128 v[214:217], v155 offset:34816
	ds_read_b128 v[218:221], v155 offset:35840
	ds_read_b128 v[222:225], v155 offset:36864
	ds_read_b128 v[226:229], v155 offset:37888
	ds_read_b128 v[230:233], v155 offset:38912
	ds_read_b128 v[234:237], v155 offset:39936
	global_load_lds_dwordx4 v138, s[46:47]
	s_mov_b32 m0, s80
	s_nop 0
	global_load_lds_dwordx4 v140, s[46:47]
	s_waitcnt vmcnt(8)
	s_waitcnt lgkmcnt(0)
	s_setprio 1
	s_waitcnt lgkmcnt(0)
	v_mfma_f32_16x16x32_bf16 v[126:129], v[130:133], v[206:209], v[126:129]
	v_mfma_f32_16x16x32_bf16 v[122:125], v[150:153], v[206:209], v[122:125]
	v_mfma_f32_16x16x32_bf16 v[118:121], v[130:133], v[214:217], v[118:121]
	v_mfma_f32_16x16x32_bf16 v[114:117], v[150:153], v[214:217], v[114:117]
	s_barrier
	v_mfma_f32_16x16x32_bf16 v[110:113], v[130:133], v[222:225], v[110:113]
	v_mfma_f32_16x16x32_bf16 v[106:109], v[150:153], v[222:225], v[106:109]
	v_mfma_f32_16x16x32_bf16 v[102:105], v[130:133], v[230:233], v[102:105]
	v_mfma_f32_16x16x32_bf16 v[98:101], v[150:153], v[230:233], v[98:101]
	v_mfma_f32_16x16x32_bf16 v[126:129], v[134:137], v[210:213], v[126:129]
	v_mfma_f32_16x16x32_bf16 v[122:125], v[156:159], v[210:213], v[122:125]
	v_mfma_f32_16x16x32_bf16 v[118:121], v[134:137], v[218:221], v[118:121]
	v_mfma_f32_16x16x32_bf16 v[114:117], v[156:159], v[218:221], v[114:117]
	v_mfma_f32_16x16x32_bf16 v[110:113], v[134:137], v[226:229], v[110:113]
	v_mfma_f32_16x16x32_bf16 v[106:109], v[156:159], v[226:229], v[106:109]
	v_mfma_f32_16x16x32_bf16 v[102:105], v[134:137], v[234:237], v[102:105]
	v_mfma_f32_16x16x32_bf16 v[98:101], v[156:159], v[234:237], v[98:101]
	s_setprio 0
	s_setprio 1
	v_mfma_f32_16x16x32_bf16 v[66:69], v[160:163], v[206:209], v[66:69]
	v_mfma_f32_16x16x32_bf16 v[58:61], v[182:185], v[206:209], v[58:61]
	v_mfma_f32_16x16x32_bf16 v[54:57], v[160:163], v[214:217], v[54:57]
	v_mfma_f32_16x16x32_bf16 v[50:53], v[182:185], v[214:217], v[50:53]
	v_mfma_f32_16x16x32_bf16 v[46:49], v[160:163], v[222:225], v[46:49]
	v_mfma_f32_16x16x32_bf16 v[42:45], v[182:185], v[222:225], v[42:45]
	v_mfma_f32_16x16x32_bf16 v[38:41], v[160:163], v[230:233], v[38:41]
	v_mfma_f32_16x16x32_bf16 v[34:37], v[182:185], v[230:233], v[34:37]
	v_mfma_f32_16x16x32_bf16 v[66:69], v[178:181], v[210:213], v[66:69]
	v_mfma_f32_16x16x32_bf16 v[58:61], v[186:189], v[210:213], v[58:61]
	v_mfma_f32_16x16x32_bf16 v[54:57], v[178:181], v[218:221], v[54:57]
	v_mfma_f32_16x16x32_bf16 v[50:53], v[186:189], v[218:221], v[50:53]
	v_mfma_f32_16x16x32_bf16 v[46:49], v[178:181], v[226:229], v[46:49]
	v_mfma_f32_16x16x32_bf16 v[42:45], v[186:189], v[226:229], v[42:45]
	v_mfma_f32_16x16x32_bf16 v[38:41], v[178:181], v[234:237], v[38:41]
	v_mfma_f32_16x16x32_bf16 v[34:37], v[186:189], v[234:237], v[34:37]
	s_setprio 0
	s_barrier
	s_add_i32 s46, s48, s77
	s_mov_b32 m0, s46
	ds_read_b128 v[206:209], v155 offset:49152
	ds_read_b128 v[210:213], v155 offset:50176
	ds_read_b128 v[214:217], v155 offset:51200
	ds_read_b128 v[218:221], v155 offset:52224
	ds_read_b128 v[222:225], v155 offset:53248
	ds_read_b128 v[226:229], v155 offset:54272
	ds_read_b128 v[230:233], v155 offset:55296
	ds_read_b128 v[234:237], v155 offset:56320
	s_add_u32 s100, s60, 128
	s_addc_u32 s101, s61, 0
	global_load_lds_dwordx4 v166, s[100:101]
	s_add_i32 m0, s46, 0x2000
	s_add_u32 s46, s60, 0x80080
	s_addc_u32 s47, s61, 0
	s_add_i32 s48, s49, s77
	s_add_u32 s100, s60, 128
	s_addc_u32 s101, s61, 0
	global_load_lds_dwordx4 v142, s[100:101]
	s_mov_b32 m0, s48
	s_nop 0
	global_load_lds_dwordx4 v166, s[46:47]
	s_add_i32 m0, s48, 0x2000
	s_nop 0
	global_load_lds_dwordx4 v142, s[46:47]
	s_mov_b32 m0, s26
	s_nop 0
	s_add_u32 s100, s70, 128
	s_addc_u32 s101, s71, 0
	global_load_lds_dwordx4 v138, s[100:101]
	s_mov_b32 m0, s81
	s_nop 0
	s_add_u32 s100, s70, 128
	s_addc_u32 s101, s71, 0
	global_load_lds_dwordx4 v140, s[100:101]
	s_waitcnt vmcnt(8)
	s_waitcnt lgkmcnt(0)
	s_setprio 1
	s_waitcnt lgkmcnt(0)
	v_mfma_f32_16x16x32_bf16 v[94:97], v[130:133], v[206:209], v[94:97]
	v_mfma_f32_16x16x32_bf16 v[90:93], v[150:153], v[206:209], v[90:93]
	v_mfma_f32_16x16x32_bf16 v[86:89], v[130:133], v[214:217], v[86:89]
	v_mfma_f32_16x16x32_bf16 v[82:85], v[150:153], v[214:217], v[82:85]
	s_barrier
	v_mfma_f32_16x16x32_bf16 v[78:81], v[130:133], v[222:225], v[78:81]
	v_mfma_f32_16x16x32_bf16 v[74:77], v[150:153], v[222:225], v[74:77]
	v_mfma_f32_16x16x32_bf16 v[70:73], v[130:133], v[230:233], v[70:73]
	v_mfma_f32_16x16x32_bf16 v[62:65], v[150:153], v[230:233], v[62:65]
	v_mfma_f32_16x16x32_bf16 v[94:97], v[134:137], v[210:213], v[94:97]
	v_mfma_f32_16x16x32_bf16 v[90:93], v[156:159], v[210:213], v[90:93]
	v_mfma_f32_16x16x32_bf16 v[86:89], v[134:137], v[218:221], v[86:89]
	v_mfma_f32_16x16x32_bf16 v[82:85], v[156:159], v[218:221], v[82:85]
	v_mfma_f32_16x16x32_bf16 v[78:81], v[134:137], v[226:229], v[78:81]
	v_mfma_f32_16x16x32_bf16 v[74:77], v[156:159], v[226:229], v[74:77]
	v_mfma_f32_16x16x32_bf16 v[70:73], v[134:137], v[234:237], v[70:73]
	v_mfma_f32_16x16x32_bf16 v[62:65], v[156:159], v[234:237], v[62:65]
	s_setprio 0
	s_setprio 1
	v_mfma_f32_16x16x32_bf16 v[30:33], v[160:163], v[206:209], v[30:33]
	v_mfma_f32_16x16x32_bf16 v[26:29], v[182:185], v[206:209], v[26:29]
	v_mfma_f32_16x16x32_bf16 v[22:25], v[160:163], v[214:217], v[22:25]
	v_mfma_f32_16x16x32_bf16 v[18:21], v[182:185], v[214:217], v[18:21]
	v_mfma_f32_16x16x32_bf16 v[14:17], v[160:163], v[222:225], v[14:17]
	v_mfma_f32_16x16x32_bf16 v[10:13], v[182:185], v[222:225], v[10:13]
	v_mfma_f32_16x16x32_bf16 v[6:9], v[160:163], v[230:233], v[6:9]
	v_mfma_f32_16x16x32_bf16 v[2:5], v[182:185], v[230:233], v[2:5]
	v_mfma_f32_16x16x32_bf16 v[30:33], v[178:181], v[210:213], v[30:33]
	v_mfma_f32_16x16x32_bf16 v[26:29], v[186:189], v[210:213], v[26:29]
	v_mfma_f32_16x16x32_bf16 v[22:25], v[178:181], v[218:221], v[22:25]
	v_mfma_f32_16x16x32_bf16 v[18:21], v[186:189], v[218:221], v[18:21]
	v_mfma_f32_16x16x32_bf16 v[14:17], v[178:181], v[226:229], v[14:17]
	v_mfma_f32_16x16x32_bf16 v[10:13], v[186:189], v[226:229], v[10:13]
	v_mfma_f32_16x16x32_bf16 v[6:9], v[178:181], v[234:237], v[6:9]
	v_mfma_f32_16x16x32_bf16 v[2:5], v[186:189], v[234:237], v[2:5]
	s_setprio 0
	s_barrier
	s_add_i32 s87, s87, 2
	s_add_u32 s68, s68, 0x100
	s_addc_u32 s69, s69, 0
	s_add_u32 s85, s85, 0x100
	s_addc_u32 s86, s86, 0
	s_cmp_gt_u32 s87, 29
	s_cbranch_scc0 .LBB0_795
	s_and_b64 vcc, exec, s[12:13]
	s_cbranch_vccz .LBB0_798
	s_barrier

.LBB0_819:
	s_add_i32 s93, s60, 2
	s_add_u32 s46, s72, 0x80
	s_addc_u32 s47, s73, 0
	s_add_i32 s48, 0, 0x10000
	s_cmp_eq_u32 s87, s60
	s_cselect_b32 s61, s23, s47
	s_cselect_b32 s60, s64, s46
	s_cselect_b32 s47, s21, s92
	s_cselect_b32 s46, s90, s91
	s_add_i32 s49, 0, 0x14000
	v_add_u32_e32 v142, s48, v205
	v_add_u32_e32 v182, s49, v205
	ds_read_b128 v[130:133], v142
	ds_read_b128 v[134:137], v142 offset:1024
	ds_read_b128 v[138:141], v142 offset:2048
	ds_read_b128 v[142:145], v142 offset:3072
	ds_read_b128 v[146:149], v182
	ds_read_b128 v[150:153], v182 offset:1024
	ds_read_b128 v[178:181], v182 offset:2048
	ds_read_b128 v[182:185], v182 offset:3072
	v_lshl_add_u64 v[236:237], s[72:73], 0, v[162:163]
	s_add_i32 m0, s71, 0xc000
	ds_read_b128 v[186:189], v207
	ds_read_b128 v[208:211], v207 offset:1024
	ds_read_b128 v[212:215], v207 offset:2048
	ds_read_b128 v[216:219], v207 offset:3072
	ds_read_b128 v[220:223], v207 offset:4096
	ds_read_b128 v[224:227], v207 offset:5120
	ds_read_b128 v[228:231], v207 offset:6144
	ds_read_b128 v[232:235], v207 offset:7168
	global_load_lds_dwordx4 v[236:237], off
	v_lshl_add_u64 v[236:237], s[72:73], 0, v[164:165]
	s_add_i32 m0, s71, 0xe000
	s_nop 0
	global_load_lds_dwordx4 v[236:237], off
	s_waitcnt vmcnt(8)
	s_waitcnt lgkmcnt(0)
	s_setprio 1
	s_waitcnt lgkmcnt(0)
	v_mfma_f32_16x16x32_bf16 v[126:129], v[130:133], v[186:189], v[126:129]
	v_mfma_f32_16x16x32_bf16 v[122:125], v[138:141], v[186:189], v[122:125]
	v_mfma_f32_16x16x32_bf16 v[118:121], v[130:133], v[212:215], v[118:121]
	v_mfma_f32_16x16x32_bf16 v[114:117], v[138:141], v[212:215], v[114:117]
	s_barrier
	v_mfma_f32_16x16x32_bf16 v[110:113], v[130:133], v[220:223], v[110:113]
	v_mfma_f32_16x16x32_bf16 v[106:109], v[138:141], v[220:223], v[106:109]
	v_mfma_f32_16x16x32_bf16 v[102:105], v[130:133], v[228:231], v[102:105]
	v_mfma_f32_16x16x32_bf16 v[98:101], v[138:141], v[228:231], v[98:101]
	v_mfma_f32_16x16x32_bf16 v[126:129], v[134:137], v[208:211], v[126:129]
	v_mfma_f32_16x16x32_bf16 v[122:125], v[142:145], v[208:211], v[122:125]
	v_mfma_f32_16x16x32_bf16 v[118:121], v[134:137], v[216:219], v[118:121]
	v_mfma_f32_16x16x32_bf16 v[114:117], v[142:145], v[216:219], v[114:117]
	v_mfma_f32_16x16x32_bf16 v[110:113], v[134:137], v[224:227], v[110:113]
	v_mfma_f32_16x16x32_bf16 v[106:109], v[142:145], v[224:227], v[106:109]
	v_mfma_f32_16x16x32_bf16 v[102:105], v[134:137], v[232:235], v[102:105]
	v_mfma_f32_16x16x32_bf16 v[98:101], v[142:145], v[232:235], v[98:101]
	s_setprio 0
	s_setprio 1
	v_mfma_f32_16x16x32_bf16 v[94:97], v[146:149], v[186:189], v[94:97]
	v_mfma_f32_16x16x32_bf16 v[90:93], v[178:181], v[186:189], v[90:93]
	v_mfma_f32_16x16x32_bf16 v[86:89], v[146:149], v[212:215], v[86:89]
	v_mfma_f32_16x16x32_bf16 v[82:85], v[178:181], v[212:215], v[82:85]
	v_mfma_f32_16x16x32_bf16 v[78:81], v[146:149], v[220:223], v[78:81]
	v_mfma_f32_16x16x32_bf16 v[74:77], v[178:181], v[220:223], v[74:77]
	v_mfma_f32_16x16x32_bf16 v[70:73], v[146:149], v[228:231], v[70:73]
	v_mfma_f32_16x16x32_bf16 v[66:69], v[178:181], v[228:231], v[66:69]
	v_mfma_f32_16x16x32_bf16 v[94:97], v[150:153], v[208:211], v[94:97]
	v_mfma_f32_16x16x32_bf16 v[90:93], v[182:185], v[208:211], v[90:93]
	v_mfma_f32_16x16x32_bf16 v[86:89], v[150:153], v[216:219], v[86:89]
	v_mfma_f32_16x16x32_bf16 v[82:85], v[182:185], v[216:219], v[82:85]
	v_mfma_f32_16x16x32_bf16 v[78:81], v[150:153], v[224:227], v[78:81]
	v_mfma_f32_16x16x32_bf16 v[74:77], v[182:185], v[224:227], v[74:77]
	v_mfma_f32_16x16x32_bf16 v[70:73], v[150:153], v[232:235], v[70:73]
	v_mfma_f32_16x16x32_bf16 v[66:69], v[182:185], v[232:235], v[66:69]
	s_setprio 0
	s_barrier
	s_add_i32 s48, s48, s80
	v_lshl_add_u64 v[236:237], s[46:47], 0, v[166:167]
	s_mov_b32 m0, s48
	ds_read_b128 v[186:189], v207 offset:16384
	ds_read_b128 v[208:211], v207 offset:17408
	ds_read_b128 v[212:215], v207 offset:18432
	ds_read_b128 v[216:219], v207 offset:19456
	ds_read_b128 v[220:223], v207 offset:20480
	ds_read_b128 v[224:227], v207 offset:21504
	ds_read_b128 v[228:231], v207 offset:22528
	ds_read_b128 v[232:235], v207 offset:23552
	global_load_lds_dwordx4 v166, s[46:47]
	s_add_i32 m0, s48, 0x2000
	v_lshl_add_u64 v[242:243], s[46:47], 0, v[158:159]
	s_add_u32 s46, s46, s26
	s_addc_u32 s47, s47, 0
	s_add_i32 s48, s49, s80
	global_load_lds_dwordx4 v[242:243], off
	v_lshl_add_u64 v[244:245], s[46:47], 0, v[166:167]
	s_mov_b32 m0, s48
	v_lshl_add_u64 v[246:247], s[46:47], 0, v[158:159]
	global_load_lds_dwordx4 v166, s[46:47]
	s_add_i32 m0, s48, 0x2000
	s_nop 0
	global_load_lds_dwordx4 v158, s[46:47]
	s_mov_b32 m0, s71
	s_nop 0
	global_load_lds_dwordx4 v154, s[60:61]
	s_mov_b32 m0, s81
	s_nop 0
	global_load_lds_dwordx4 v156, s[60:61]
	s_waitcnt vmcnt(8)
	s_waitcnt lgkmcnt(0)
	s_setprio 1
	s_waitcnt lgkmcnt(0)
	v_mfma_f32_16x16x32_bf16 v[62:65], v[130:133], v[186:189], v[62:65]
	v_mfma_f32_16x16x32_bf16 v[58:61], v[138:141], v[186:189], v[58:61]
	v_mfma_f32_16x16x32_bf16 v[54:57], v[130:133], v[212:215], v[54:57]
	v_mfma_f32_16x16x32_bf16 v[50:53], v[138:141], v[212:215], v[50:53]
	s_barrier
	v_mfma_f32_16x16x32_bf16 v[46:49], v[130:133], v[220:223], v[46:49]
	v_mfma_f32_16x16x32_bf16 v[42:45], v[138:141], v[220:223], v[42:45]
	v_mfma_f32_16x16x32_bf16 v[38:41], v[130:133], v[228:231], v[38:41]
	v_mfma_f32_16x16x32_bf16 v[34:37], v[138:141], v[228:231], v[34:37]
	v_mfma_f32_16x16x32_bf16 v[62:65], v[134:137], v[208:211], v[62:65]
	v_mfma_f32_16x16x32_bf16 v[58:61], v[142:145], v[208:211], v[58:61]
	v_mfma_f32_16x16x32_bf16 v[54:57], v[134:137], v[216:219], v[54:57]
	v_mfma_f32_16x16x32_bf16 v[50:53], v[142:145], v[216:219], v[50:53]
	v_mfma_f32_16x16x32_bf16 v[46:49], v[134:137], v[224:227], v[46:49]
	v_mfma_f32_16x16x32_bf16 v[42:45], v[142:145], v[224:227], v[42:45]
	v_mfma_f32_16x16x32_bf16 v[38:41], v[134:137], v[232:235], v[38:41]
	v_mfma_f32_16x16x32_bf16 v[34:37], v[142:145], v[232:235], v[34:37]
	s_setprio 0
	s_setprio 1
	v_mfma_f32_16x16x32_bf16 v[30:33], v[146:149], v[186:189], v[30:33]
	v_mfma_f32_16x16x32_bf16 v[26:29], v[178:181], v[186:189], v[26:29]
	v_mfma_f32_16x16x32_bf16 v[22:25], v[146:149], v[212:215], v[22:25]
	v_mfma_f32_16x16x32_bf16 v[18:21], v[178:181], v[212:215], v[18:21]
	v_mfma_f32_16x16x32_bf16 v[14:17], v[146:149], v[220:223], v[14:17]
	v_mfma_f32_16x16x32_bf16 v[10:13], v[178:181], v[220:223], v[10:13]
	v_mfma_f32_16x16x32_bf16 v[6:9], v[146:149], v[228:231], v[6:9]
	v_mfma_f32_16x16x32_bf16 v[2:5], v[178:181], v[228:231], v[2:5]
	v_mfma_f32_16x16x32_bf16 v[30:33], v[150:153], v[208:211], v[30:33]
	v_mfma_f32_16x16x32_bf16 v[26:29], v[182:185], v[208:211], v[26:29]
	v_mfma_f32_16x16x32_bf16 v[22:25], v[150:153], v[216:219], v[22:25]
	v_mfma_f32_16x16x32_bf16 v[18:21], v[182:185], v[216:219], v[18:21]
	v_mfma_f32_16x16x32_bf16 v[14:17], v[150:153], v[224:227], v[14:17]
	v_mfma_f32_16x16x32_bf16 v[10:13], v[182:185], v[224:227], v[10:13]
	v_mfma_f32_16x16x32_bf16 v[6:9], v[150:153], v[232:235], v[6:9]
	v_mfma_f32_16x16x32_bf16 v[2:5], v[182:185], v[232:235], v[2:5]
	s_setprio 0
	s_barrier
	s_add_i32 s48, 0, 0x18000
	s_add_i32 s49, 0, 0x1c000
	v_add_u32_e32 v142, s48, v205
	v_add_u32_e32 v182, s49, v205
	ds_read_b128 v[130:133], v142
	ds_read_b128 v[134:137], v142 offset:1024
	ds_read_b128 v[138:141], v142 offset:2048
	ds_read_b128 v[142:145], v142 offset:3072
	ds_read_b128 v[146:149], v182
	ds_read_b128 v[150:153], v182 offset:1024
	ds_read_b128 v[178:181], v182 offset:2048
	ds_read_b128 v[182:185], v182 offset:3072
	s_add_u32 s46, s60, s26
	s_addc_u32 s47, s61, 0
	s_mov_b32 m0, s82
	ds_read_b128 v[186:189], v207 offset:32768
	ds_read_b128 v[208:211], v207 offset:33792
	ds_read_b128 v[212:215], v207 offset:34816
	ds_read_b128 v[216:219], v207 offset:35840
	ds_read_b128 v[220:223], v207 offset:36864
	ds_read_b128 v[224:227], v207 offset:37888
	ds_read_b128 v[228:231], v207 offset:38912
	ds_read_b128 v[232:235], v207 offset:39936
	global_load_lds_dwordx4 v154, s[46:47]
	s_mov_b32 m0, s83
	s_nop 0
	global_load_lds_dwordx4 v156, s[46:47]
	s_waitcnt vmcnt(8)
	s_waitcnt lgkmcnt(0)
	s_setprio 1
	s_waitcnt lgkmcnt(0)
	v_mfma_f32_16x16x32_bf16 v[126:129], v[130:133], v[186:189], v[126:129]
	v_mfma_f32_16x16x32_bf16 v[122:125], v[138:141], v[186:189], v[122:125]
	v_mfma_f32_16x16x32_bf16 v[118:121], v[130:133], v[212:215], v[118:121]
	v_mfma_f32_16x16x32_bf16 v[114:117], v[138:141], v[212:215], v[114:117]
	s_barrier
	v_mfma_f32_16x16x32_bf16 v[110:113], v[130:133], v[220:223], v[110:113]
	v_mfma_f32_16x16x32_bf16 v[106:109], v[138:141], v[220:223], v[106:109]
	v_mfma_f32_16x16x32_bf16 v[102:105], v[130:133], v[228:231], v[102:105]
	v_mfma_f32_16x16x32_bf16 v[98:101], v[138:141], v[228:231], v[98:101]
	v_mfma_f32_16x16x32_bf16 v[126:129], v[134:137], v[208:211], v[126:129]
	v_mfma_f32_16x16x32_bf16 v[122:125], v[142:145], v[208:211], v[122:125]
	v_mfma_f32_16x16x32_bf16 v[118:121], v[134:137], v[216:219], v[118:121]
	v_mfma_f32_16x16x32_bf16 v[114:117], v[142:145], v[216:219], v[114:117]
	v_mfma_f32_16x16x32_bf16 v[110:113], v[134:137], v[224:227], v[110:113]
	v_mfma_f32_16x16x32_bf16 v[106:109], v[142:145], v[224:227], v[106:109]
	v_mfma_f32_16x16x32_bf16 v[102:105], v[134:137], v[232:235], v[102:105]
	v_mfma_f32_16x16x32_bf16 v[98:101], v[142:145], v[232:235], v[98:101]
	s_setprio 0
	s_setprio 1
	v_mfma_f32_16x16x32_bf16 v[94:97], v[146:149], v[186:189], v[94:97]
	v_mfma_f32_16x16x32_bf16 v[90:93], v[178:181], v[186:189], v[90:93]
	v_mfma_f32_16x16x32_bf16 v[86:89], v[146:149], v[212:215], v[86:89]
	v_mfma_f32_16x16x32_bf16 v[82:85], v[178:181], v[212:215], v[82:85]
	v_mfma_f32_16x16x32_bf16 v[78:81], v[146:149], v[220:223], v[78:81]
	v_mfma_f32_16x16x32_bf16 v[74:77], v[178:181], v[220:223], v[74:77]
	v_mfma_f32_16x16x32_bf16 v[70:73], v[146:149], v[228:231], v[70:73]
	v_mfma_f32_16x16x32_bf16 v[66:69], v[178:181], v[228:231], v[66:69]
	v_mfma_f32_16x16x32_bf16 v[94:97], v[150:153], v[208:211], v[94:97]
	v_mfma_f32_16x16x32_bf16 v[90:93], v[182:185], v[208:211], v[90:93]
	v_mfma_f32_16x16x32_bf16 v[86:89], v[150:153], v[216:219], v[86:89]
	v_mfma_f32_16x16x32_bf16 v[82:85], v[182:185], v[216:219], v[82:85]
	v_mfma_f32_16x16x32_bf16 v[78:81], v[150:153], v[224:227], v[78:81]
	v_mfma_f32_16x16x32_bf16 v[74:77], v[182:185], v[224:227], v[74:77]
	v_mfma_f32_16x16x32_bf16 v[70:73], v[150:153], v[232:235], v[70:73]
	v_mfma_f32_16x16x32_bf16 v[66:69], v[182:185], v[232:235], v[66:69]
	s_setprio 0
	s_barrier
	s_add_i32 s46, s48, s80
	v_lshl_add_u64 v[236:237], v[236:237], 0, s[42:43]
	s_mov_b32 m0, s46
	ds_read_b128 v[186:189], v207 offset:49152
	ds_read_b128 v[208:211], v207 offset:50176
	ds_read_b128 v[212:215], v207 offset:51200
	ds_read_b128 v[216:219], v207 offset:52224
	ds_read_b128 v[220:223], v207 offset:53248
	ds_read_b128 v[224:227], v207 offset:54272
	ds_read_b128 v[228:231], v207 offset:55296
	ds_read_b128 v[232:235], v207 offset:56320
	global_load_lds_dwordx4 v[236:237], off
	v_lshl_add_u64 v[236:237], v[242:243], 0, s[42:43]
	s_add_i32 m0, s46, 0x2000
	s_add_i32 s46, s49, s80
	global_load_lds_dwordx4 v[236:237], off
	v_lshl_add_u64 v[236:237], v[244:245], 0, s[42:43]
	s_mov_b32 m0, s46
	s_nop 0
	global_load_lds_dwordx4 v[236:237], off
	v_lshl_add_u64 v[236:237], v[246:247], 0, s[42:43]
	s_add_i32 m0, s46, 0x2000
	s_nop 0
	global_load_lds_dwordx4 v[236:237], off
	s_mov_b32 m0, s85
	s_nop 0
	s_add_u32 s100, s60, 128
	s_addc_u32 s101, s61, 0
	global_load_lds_dwordx4 v154, s[100:101]
	s_mov_b32 m0, s86
	s_nop 0
	s_add_u32 s100, s60, 128
	s_addc_u32 s101, s61, 0
	global_load_lds_dwordx4 v156, s[100:101]
	s_waitcnt vmcnt(8)
	s_waitcnt lgkmcnt(0)
	s_setprio 1
	s_waitcnt lgkmcnt(0)
	v_mfma_f32_16x16x32_bf16 v[62:65], v[130:133], v[186:189], v[62:65]
	v_mfma_f32_16x16x32_bf16 v[58:61], v[138:141], v[186:189], v[58:61]
	v_mfma_f32_16x16x32_bf16 v[54:57], v[130:133], v[212:215], v[54:57]
	v_mfma_f32_16x16x32_bf16 v[50:53], v[138:141], v[212:215], v[50:53]
	s_barrier
	v_mfma_f32_16x16x32_bf16 v[46:49], v[130:133], v[220:223], v[46:49]
	v_mfma_f32_16x16x32_bf16 v[42:45], v[138:141], v[220:223], v[42:45]
	v_mfma_f32_16x16x32_bf16 v[38:41], v[130:133], v[228:231], v[38:41]
	v_mfma_f32_16x16x32_bf16 v[34:37], v[138:141], v[228:231], v[34:37]
	v_mfma_f32_16x16x32_bf16 v[62:65], v[134:137], v[208:211], v[62:65]
	v_mfma_f32_16x16x32_bf16 v[58:61], v[142:145], v[208:211], v[58:61]
	v_mfma_f32_16x16x32_bf16 v[54:57], v[134:137], v[216:219], v[54:57]
	v_mfma_f32_16x16x32_bf16 v[50:53], v[142:145], v[216:219], v[50:53]
	v_mfma_f32_16x16x32_bf16 v[46:49], v[134:137], v[224:227], v[46:49]
	v_mfma_f32_16x16x32_bf16 v[42:45], v[142:145], v[224:227], v[42:45]
	v_mfma_f32_16x16x32_bf16 v[38:41], v[134:137], v[232:235], v[38:41]
	v_mfma_f32_16x16x32_bf16 v[34:37], v[142:145], v[232:235], v[34:37]
	s_setprio 0
	s_setprio 1
	v_mfma_f32_16x16x32_bf16 v[30:33], v[146:149], v[186:189], v[30:33]
	v_mfma_f32_16x16x32_bf16 v[26:29], v[178:181], v[186:189], v[26:29]
	v_mfma_f32_16x16x32_bf16 v[22:25], v[146:149], v[212:215], v[22:25]
	v_mfma_f32_16x16x32_bf16 v[18:21], v[178:181], v[212:215], v[18:21]
	v_mfma_f32_16x16x32_bf16 v[14:17], v[146:149], v[220:223], v[14:17]
	v_mfma_f32_16x16x32_bf16 v[10:13], v[178:181], v[220:223], v[10:13]
	v_mfma_f32_16x16x32_bf16 v[6:9], v[146:149], v[228:231], v[6:9]
	v_mfma_f32_16x16x32_bf16 v[2:5], v[178:181], v[228:231], v[2:5]
	v_mfma_f32_16x16x32_bf16 v[30:33], v[150:153], v[208:211], v[30:33]
	v_mfma_f32_16x16x32_bf16 v[26:29], v[182:185], v[208:211], v[26:29]
	v_mfma_f32_16x16x32_bf16 v[22:25], v[150:153], v[216:219], v[22:25]
	v_mfma_f32_16x16x32_bf16 v[18:21], v[182:185], v[216:219], v[18:21]
	v_mfma_f32_16x16x32_bf16 v[14:17], v[150:153], v[224:227], v[14:17]
	v_mfma_f32_16x16x32_bf16 v[10:13], v[182:185], v[224:227], v[10:13]
	v_mfma_f32_16x16x32_bf16 v[6:9], v[150:153], v[232:235], v[6:9]
	v_mfma_f32_16x16x32_bf16 v[2:5], v[182:185], v[232:235], v[2:5]
	s_setprio 0
	s_barrier
	s_add_u32 s72, s72, 0x100
	s_addc_u32 s73, s73, 0
	s_add_u32 s91, s91, 0x100
	s_addc_u32 s92, s92, 0
	s_cmp_ge_u32 s93, s84
	s_mov_b32 s60, s93
	s_cbranch_scc0 .LBB0_819
	s_and_b64 vcc, exec, s[18:19]
	s_cbranch_vccz .LBB0_822
	s_barrier

.LBB0_903:
	s_add_u32 s46, s66, 0xfff80080
	s_addc_u32 s47, s67, -1
	s_add_i32 s48, 0, 0x10000
	s_cmp_eq_u32 s84, 28
	s_cselect_b32 s69, s17, s47
	s_cselect_b32 s68, s64, s46
	s_cselect_b32 s61, s13, s83
	s_cselect_b32 s60, s81, s82
	s_add_i32 s49, 0, 0x14000
	v_add_u32_e32 v142, s48, v186
	v_add_u32_e32 v164, s49, v186
	ds_read_b128 v[130:133], v142
	ds_read_b128 v[134:137], v142 offset:1024
	ds_read_b128 v[138:141], v142 offset:2048
	ds_read_b128 v[142:145], v142 offset:3072
	ds_read_b128 v[146:149], v164
	ds_read_b128 v[160:163], v164 offset:1024
	ds_read_b128 v[178:181], v164 offset:2048
	ds_read_b128 v[182:185], v164 offset:3072
	s_add_i32 m0, s74, 0xc000
	ds_read_b128 v[206:209], v188
	ds_read_b128 v[210:213], v188 offset:1024
	ds_read_b128 v[214:217], v188 offset:2048
	ds_read_b128 v[218:221], v188 offset:3072
	ds_read_b128 v[222:225], v188 offset:4096
	ds_read_b128 v[226:229], v188 offset:5120
	ds_read_b128 v[230:233], v188 offset:6144
	ds_read_b128 v[234:237], v188 offset:7168
	global_load_lds_dwordx4 v156, s[66:67]
	s_add_i32 m0, s74, 0xe000
	s_nop 0
	global_load_lds_dwordx4 v158, s[66:67]
	s_waitcnt vmcnt(8)
	s_waitcnt lgkmcnt(0)
	s_setprio 1
	s_waitcnt lgkmcnt(0)
	v_mfma_f32_16x16x32_bf16 v[126:129], v[130:133], v[206:209], v[126:129]
	v_mfma_f32_16x16x32_bf16 v[122:125], v[138:141], v[206:209], v[122:125]
	v_mfma_f32_16x16x32_bf16 v[118:121], v[130:133], v[214:217], v[118:121]
	v_mfma_f32_16x16x32_bf16 v[110:113], v[138:141], v[214:217], v[110:113]
	s_barrier
	v_mfma_f32_16x16x32_bf16 v[94:97], v[130:133], v[222:225], v[94:97]
	v_mfma_f32_16x16x32_bf16 v[90:93], v[138:141], v[222:225], v[90:93]
	v_mfma_f32_16x16x32_bf16 v[82:85], v[130:133], v[230:233], v[82:85]
	v_mfma_f32_16x16x32_bf16 v[74:77], v[138:141], v[230:233], v[74:77]
	v_mfma_f32_16x16x32_bf16 v[126:129], v[134:137], v[210:213], v[126:129]
	v_mfma_f32_16x16x32_bf16 v[122:125], v[142:145], v[210:213], v[122:125]
	v_mfma_f32_16x16x32_bf16 v[118:121], v[134:137], v[218:221], v[118:121]
	v_mfma_f32_16x16x32_bf16 v[110:113], v[142:145], v[218:221], v[110:113]
	v_mfma_f32_16x16x32_bf16 v[94:97], v[134:137], v[226:229], v[94:97]
	v_mfma_f32_16x16x32_bf16 v[90:93], v[142:145], v[226:229], v[90:93]
	v_mfma_f32_16x16x32_bf16 v[82:85], v[134:137], v[234:237], v[82:85]
	v_mfma_f32_16x16x32_bf16 v[74:77], v[142:145], v[234:237], v[74:77]
	s_setprio 0
	s_setprio 1
	v_mfma_f32_16x16x32_bf16 v[114:117], v[146:149], v[206:209], v[114:117]
	v_mfma_f32_16x16x32_bf16 v[106:109], v[178:181], v[206:209], v[106:109]
	v_mfma_f32_16x16x32_bf16 v[102:105], v[146:149], v[214:217], v[102:105]
	v_mfma_f32_16x16x32_bf16 v[98:101], v[178:181], v[214:217], v[98:101]
	v_mfma_f32_16x16x32_bf16 v[86:89], v[146:149], v[222:225], v[86:89]
	v_mfma_f32_16x16x32_bf16 v[78:81], v[178:181], v[222:225], v[78:81]
	v_mfma_f32_16x16x32_bf16 v[70:73], v[146:149], v[230:233], v[70:73]
	v_mfma_f32_16x16x32_bf16 v[66:69], v[178:181], v[230:233], v[66:69]
	v_mfma_f32_16x16x32_bf16 v[114:117], v[160:163], v[210:213], v[114:117]
	v_mfma_f32_16x16x32_bf16 v[106:109], v[182:185], v[210:213], v[106:109]
	v_mfma_f32_16x16x32_bf16 v[102:105], v[160:163], v[218:221], v[102:105]
	v_mfma_f32_16x16x32_bf16 v[98:101], v[182:185], v[218:221], v[98:101]
	v_mfma_f32_16x16x32_bf16 v[86:89], v[160:163], v[226:229], v[86:89]
	v_mfma_f32_16x16x32_bf16 v[78:81], v[182:185], v[226:229], v[78:81]
	v_mfma_f32_16x16x32_bf16 v[70:73], v[160:163], v[234:237], v[70:73]
	v_mfma_f32_16x16x32_bf16 v[66:69], v[182:185], v[234:237], v[66:69]
	s_setprio 0
	s_barrier
	s_add_i32 s46, s48, s73
	s_mov_b32 m0, s46
	ds_read_b128 v[206:209], v188 offset:16384
	ds_read_b128 v[210:213], v188 offset:17408
	ds_read_b128 v[214:217], v188 offset:18432
	ds_read_b128 v[218:221], v188 offset:19456
	ds_read_b128 v[222:225], v188 offset:20480
	ds_read_b128 v[226:229], v188 offset:21504
	ds_read_b128 v[230:233], v188 offset:22528
	ds_read_b128 v[234:237], v188 offset:23552
	global_load_lds_dwordx4 v166, s[60:61]
	s_add_i32 m0, s46, 0x2000
	s_add_u32 s46, s60, 0x80000
	s_addc_u32 s47, s61, 0
	s_add_i32 s48, s49, s73
	global_load_lds_dwordx4 v154, s[60:61]
	s_mov_b32 m0, s48
	s_nop 0
	global_load_lds_dwordx4 v166, s[46:47]
	s_add_i32 m0, s48, 0x2000
	s_nop 0
	global_load_lds_dwordx4 v154, s[46:47]
	s_mov_b32 m0, s74
	s_nop 0
	global_load_lds_dwordx4 v150, s[68:69]
	s_mov_b32 m0, s75
	s_nop 0
	global_load_lds_dwordx4 v152, s[68:69]
	s_waitcnt vmcnt(8)
	s_waitcnt lgkmcnt(0)
	s_setprio 1
	s_waitcnt lgkmcnt(0)
	v_mfma_f32_16x16x32_bf16 v[62:65], v[130:133], v[206:209], v[62:65]
	v_mfma_f32_16x16x32_bf16 v[58:61], v[138:141], v[206:209], v[58:61]
	v_mfma_f32_16x16x32_bf16 v[50:53], v[130:133], v[214:217], v[50:53]
	v_mfma_f32_16x16x32_bf16 v[42:45], v[138:141], v[214:217], v[42:45]
	s_barrier
	v_mfma_f32_16x16x32_bf16 v[34:37], v[130:133], v[222:225], v[34:37]
	v_mfma_f32_16x16x32_bf16 v[26:29], v[138:141], v[222:225], v[26:29]
	v_mfma_f32_16x16x32_bf16 v[18:21], v[130:133], v[230:233], v[18:21]
	v_mfma_f32_16x16x32_bf16 v[10:13], v[138:141], v[230:233], v[10:13]
	v_mfma_f32_16x16x32_bf16 v[62:65], v[134:137], v[210:213], v[62:65]
	v_mfma_f32_16x16x32_bf16 v[58:61], v[142:145], v[210:213], v[58:61]
	v_mfma_f32_16x16x32_bf16 v[50:53], v[134:137], v[218:221], v[50:53]
	v_mfma_f32_16x16x32_bf16 v[42:45], v[142:145], v[218:221], v[42:45]
	v_mfma_f32_16x16x32_bf16 v[34:37], v[134:137], v[226:229], v[34:37]
	v_mfma_f32_16x16x32_bf16 v[26:29], v[142:145], v[226:229], v[26:29]
	v_mfma_f32_16x16x32_bf16 v[18:21], v[134:137], v[234:237], v[18:21]
	v_mfma_f32_16x16x32_bf16 v[10:13], v[142:145], v[234:237], v[10:13]
	s_setprio 0
	s_setprio 1
	v_mfma_f32_16x16x32_bf16 v[54:57], v[146:149], v[206:209], v[54:57]
	v_mfma_f32_16x16x32_bf16 v[46:49], v[178:181], v[206:209], v[46:49]
	v_mfma_f32_16x16x32_bf16 v[38:41], v[146:149], v[214:217], v[38:41]
	v_mfma_f32_16x16x32_bf16 v[30:33], v[178:181], v[214:217], v[30:33]
	v_mfma_f32_16x16x32_bf16 v[22:25], v[146:149], v[222:225], v[22:25]
	v_mfma_f32_16x16x32_bf16 v[14:17], v[178:181], v[222:225], v[14:17]
	v_mfma_f32_16x16x32_bf16 v[6:9], v[146:149], v[230:233], v[6:9]
	v_mfma_f32_16x16x32_bf16 v[2:5], v[178:181], v[230:233], v[2:5]
	v_mfma_f32_16x16x32_bf16 v[54:57], v[160:163], v[210:213], v[54:57]
	v_mfma_f32_16x16x32_bf16 v[46:49], v[182:185], v[210:213], v[46:49]
	v_mfma_f32_16x16x32_bf16 v[38:41], v[160:163], v[218:221], v[38:41]
	v_mfma_f32_16x16x32_bf16 v[30:33], v[182:185], v[218:221], v[30:33]
	v_mfma_f32_16x16x32_bf16 v[22:25], v[160:163], v[226:229], v[22:25]
	v_mfma_f32_16x16x32_bf16 v[14:17], v[182:185], v[226:229], v[14:17]
	v_mfma_f32_16x16x32_bf16 v[6:9], v[160:163], v[234:237], v[6:9]
	v_mfma_f32_16x16x32_bf16 v[2:5], v[182:185], v[234:237], v[2:5]
	s_setprio 0
	s_barrier
	s_add_i32 s48, 0, 0x18000
	s_add_i32 s49, 0, 0x1c000
	v_add_u32_e32 v142, s48, v186
	v_add_u32_e32 v182, s49, v186
	ds_read_b128 v[130:133], v142
	ds_read_b128 v[134:137], v142 offset:1024
	ds_read_b128 v[138:141], v142 offset:2048
	ds_read_b128 v[142:145], v142 offset:3072
	ds_read_b128 v[146:149], v182
	ds_read_b128 v[160:163], v182 offset:1024
	ds_read_b128 v[178:181], v182 offset:2048
	ds_read_b128 v[182:185], v182 offset:3072
	s_add_u32 s46, s68, 0x80000
	s_addc_u32 s47, s69, 0
	s_mov_b32 m0, s76
	ds_read_b128 v[206:209], v188 offset:32768
	ds_read_b128 v[210:213], v188 offset:33792
	ds_read_b128 v[214:217], v188 offset:34816
	ds_read_b128 v[218:221], v188 offset:35840
	ds_read_b128 v[222:225], v188 offset:36864
	ds_read_b128 v[226:229], v188 offset:37888
	ds_read_b128 v[230:233], v188 offset:38912
	ds_read_b128 v[234:237], v188 offset:39936
	global_load_lds_dwordx4 v150, s[46:47]
	s_mov_b32 m0, s77
	s_nop 0
	global_load_lds_dwordx4 v152, s[46:47]
	s_waitcnt vmcnt(8)
	s_waitcnt lgkmcnt(0)
	s_setprio 1
	s_waitcnt lgkmcnt(0)
	v_mfma_f32_16x16x32_bf16 v[126:129], v[130:133], v[206:209], v[126:129]
	v_mfma_f32_16x16x32_bf16 v[122:125], v[138:141], v[206:209], v[122:125]
	v_mfma_f32_16x16x32_bf16 v[118:121], v[130:133], v[214:217], v[118:121]
	v_mfma_f32_16x16x32_bf16 v[110:113], v[138:141], v[214:217], v[110:113]
	s_barrier
	v_mfma_f32_16x16x32_bf16 v[94:97], v[130:133], v[222:225], v[94:97]
	v_mfma_f32_16x16x32_bf16 v[90:93], v[138:141], v[222:225], v[90:93]
	v_mfma_f32_16x16x32_bf16 v[82:85], v[130:133], v[230:233], v[82:85]
	v_mfma_f32_16x16x32_bf16 v[74:77], v[138:141], v[230:233], v[74:77]
	v_mfma_f32_16x16x32_bf16 v[126:129], v[134:137], v[210:213], v[126:129]
	v_mfma_f32_16x16x32_bf16 v[122:125], v[142:145], v[210:213], v[122:125]
	v_mfma_f32_16x16x32_bf16 v[118:121], v[134:137], v[218:221], v[118:121]
	v_mfma_f32_16x16x32_bf16 v[110:113], v[142:145], v[218:221], v[110:113]
	v_mfma_f32_16x16x32_bf16 v[94:97], v[134:137], v[226:229], v[94:97]
	v_mfma_f32_16x16x32_bf16 v[90:93], v[142:145], v[226:229], v[90:93]
	v_mfma_f32_16x16x32_bf16 v[82:85], v[134:137], v[234:237], v[82:85]
	v_mfma_f32_16x16x32_bf16 v[74:77], v[142:145], v[234:237], v[74:77]
	s_setprio 0
	s_setprio 1
	v_mfma_f32_16x16x32_bf16 v[114:117], v[146:149], v[206:209], v[114:117]
	v_mfma_f32_16x16x32_bf16 v[106:109], v[178:181], v[206:209], v[106:109]
	v_mfma_f32_16x16x32_bf16 v[102:105], v[146:149], v[214:217], v[102:105]
	v_mfma_f32_16x16x32_bf16 v[98:101], v[178:181], v[214:217], v[98:101]
	v_mfma_f32_16x16x32_bf16 v[86:89], v[146:149], v[222:225], v[86:89]
	v_mfma_f32_16x16x32_bf16 v[78:81], v[178:181], v[222:225], v[78:81]
	v_mfma_f32_16x16x32_bf16 v[70:73], v[146:149], v[230:233], v[70:73]
	v_mfma_f32_16x16x32_bf16 v[66:69], v[178:181], v[230:233], v[66:69]
	v_mfma_f32_16x16x32_bf16 v[114:117], v[160:163], v[210:213], v[114:117]
	v_mfma_f32_16x16x32_bf16 v[106:109], v[182:185], v[210:213], v[106:109]
	v_mfma_f32_16x16x32_bf16 v[102:105], v[160:163], v[218:221], v[102:105]
	v_mfma_f32_16x16x32_bf16 v[98:101], v[182:185], v[218:221], v[98:101]
	v_mfma_f32_16x16x32_bf16 v[86:89], v[160:163], v[226:229], v[86:89]
	v_mfma_f32_16x16x32_bf16 v[78:81], v[182:185], v[226:229], v[78:81]
	v_mfma_f32_16x16x32_bf16 v[70:73], v[160:163], v[234:237], v[70:73]
	v_mfma_f32_16x16x32_bf16 v[66:69], v[182:185], v[234:237], v[66:69]
	s_setprio 0
	s_barrier
	s_add_i32 s46, s48, s73
	s_mov_b32 m0, s46
	ds_read_b128 v[206:209], v188 offset:49152
	ds_read_b128 v[210:213], v188 offset:50176
	ds_read_b128 v[214:217], v188 offset:51200
	ds_read_b128 v[218:221], v188 offset:52224
	ds_read_b128 v[222:225], v188 offset:53248
	ds_read_b128 v[226:229], v188 offset:54272
	ds_read_b128 v[230:233], v188 offset:55296
	ds_read_b128 v[234:237], v188 offset:56320
	s_add_u32 s100, s60, 128
	s_addc_u32 s101, s61, 0
	global_load_lds_dwordx4 v166, s[100:101]
	s_add_i32 m0, s46, 0x2000
	s_add_u32 s46, s60, 0x80080
	s_addc_u32 s47, s61, 0
	s_add_i32 s48, s49, s73
	s_add_u32 s100, s60, 128
	s_addc_u32 s101, s61, 0
	global_load_lds_dwordx4 v154, s[100:101]
	s_mov_b32 m0, s48
	s_nop 0
	global_load_lds_dwordx4 v166, s[46:47]
	s_add_i32 m0, s48, 0x2000
	s_nop 0
	global_load_lds_dwordx4 v154, s[46:47]
	s_mov_b32 m0, s78
	s_nop 0
	s_add_u32 s100, s68, 128
	s_addc_u32 s101, s69, 0
	global_load_lds_dwordx4 v150, s[100:101]
	s_mov_b32 m0, s79
	s_nop 0
	s_add_u32 s100, s68, 128
	s_addc_u32 s101, s69, 0
	global_load_lds_dwordx4 v152, s[100:101]
	s_waitcnt vmcnt(8)
	s_waitcnt lgkmcnt(0)
	s_setprio 1
	s_waitcnt lgkmcnt(0)
	v_mfma_f32_16x16x32_bf16 v[62:65], v[130:133], v[206:209], v[62:65]
	v_mfma_f32_16x16x32_bf16 v[58:61], v[138:141], v[206:209], v[58:61]
	v_mfma_f32_16x16x32_bf16 v[50:53], v[130:133], v[214:217], v[50:53]
	v_mfma_f32_16x16x32_bf16 v[42:45], v[138:141], v[214:217], v[42:45]
	s_barrier
	v_mfma_f32_16x16x32_bf16 v[34:37], v[130:133], v[222:225], v[34:37]
	v_mfma_f32_16x16x32_bf16 v[26:29], v[138:141], v[222:225], v[26:29]
	v_mfma_f32_16x16x32_bf16 v[18:21], v[130:133], v[230:233], v[18:21]
	v_mfma_f32_16x16x32_bf16 v[10:13], v[138:141], v[230:233], v[10:13]
	v_mfma_f32_16x16x32_bf16 v[62:65], v[134:137], v[210:213], v[62:65]
	v_mfma_f32_16x16x32_bf16 v[58:61], v[142:145], v[210:213], v[58:61]
	v_mfma_f32_16x16x32_bf16 v[50:53], v[134:137], v[218:221], v[50:53]
	v_mfma_f32_16x16x32_bf16 v[42:45], v[142:145], v[218:221], v[42:45]
	v_mfma_f32_16x16x32_bf16 v[34:37], v[134:137], v[226:229], v[34:37]
	v_mfma_f32_16x16x32_bf16 v[26:29], v[142:145], v[226:229], v[26:29]
	v_mfma_f32_16x16x32_bf16 v[18:21], v[134:137], v[234:237], v[18:21]
	v_mfma_f32_16x16x32_bf16 v[10:13], v[142:145], v[234:237], v[10:13]
	s_setprio 0
	s_setprio 1
	v_mfma_f32_16x16x32_bf16 v[54:57], v[146:149], v[206:209], v[54:57]
	v_mfma_f32_16x16x32_bf16 v[46:49], v[178:181], v[206:209], v[46:49]
	v_mfma_f32_16x16x32_bf16 v[38:41], v[146:149], v[214:217], v[38:41]
	v_mfma_f32_16x16x32_bf16 v[30:33], v[178:181], v[214:217], v[30:33]
	v_mfma_f32_16x16x32_bf16 v[22:25], v[146:149], v[222:225], v[22:25]
	v_mfma_f32_16x16x32_bf16 v[14:17], v[178:181], v[222:225], v[14:17]
	v_mfma_f32_16x16x32_bf16 v[6:9], v[146:149], v[230:233], v[6:9]
	v_mfma_f32_16x16x32_bf16 v[2:5], v[178:181], v[230:233], v[2:5]
	v_mfma_f32_16x16x32_bf16 v[54:57], v[160:163], v[210:213], v[54:57]
	v_mfma_f32_16x16x32_bf16 v[46:49], v[182:185], v[210:213], v[46:49]
	v_mfma_f32_16x16x32_bf16 v[38:41], v[160:163], v[218:221], v[38:41]
	v_mfma_f32_16x16x32_bf16 v[30:33], v[182:185], v[218:221], v[30:33]
	v_mfma_f32_16x16x32_bf16 v[22:25], v[160:163], v[226:229], v[22:25]
	v_mfma_f32_16x16x32_bf16 v[14:17], v[182:185], v[226:229], v[14:17]
	v_mfma_f32_16x16x32_bf16 v[6:9], v[160:163], v[234:237], v[6:9]
	v_mfma_f32_16x16x32_bf16 v[2:5], v[182:185], v[234:237], v[2:5]
	s_setprio 0
	s_barrier
	s_add_i32 s84, s84, 2
	s_add_u32 s66, s66, 0x100
	s_addc_u32 s67, s67, 0
	s_add_u32 s82, s82, 0x100
	s_addc_u32 s83, s83, 0
	s_cmp_gt_u32 s84, 29
	s_cbranch_scc0 .LBB0_903
	s_and_b64 vcc, exec, s[10:11]
	s_cbranch_vccz .LBB0_906
	s_barrier

.LBB0_1035:
	s_add_u32 s46, s64, 0xfff80080
	s_addc_u32 s47, s65, -1
	s_add_i32 s48, 0, 0x10000
	s_cmp_eq_u32 s84, 28
	s_cselect_b32 s67, s17, s47
	s_cselect_b32 s66, s80, s46
	v_add_u32_e32 v140, s48, v142
	s_cselect_b32 s61, s13, s83
	s_cselect_b32 s60, s81, s82
	s_add_i32 s49, 0, 0x14000
	ds_read_b128 v[146:149], v140
	ds_read_b128 v[150:153], v140 offset:1024
	ds_read_b128 v[154:157], v140 offset:2048
	ds_read_b128 v[158:161], v140 offset:3072
	v_add_u32_e32 v140, s49, v142
	ds_read_b128 v[162:165], v140
	ds_read_b128 v[178:181], v140 offset:1024
	ds_read_b128 v[182:185], v140 offset:2048
	ds_read_b128 v[186:189], v140 offset:3072
	s_add_i32 m0, s23, 0xc000
	ds_read_b128 v[206:209], v144
	ds_read_b128 v[210:213], v144 offset:1024
	ds_read_b128 v[214:217], v144 offset:2048
	ds_read_b128 v[218:221], v144 offset:3072
	ds_read_b128 v[222:225], v144 offset:4096
	ds_read_b128 v[226:229], v144 offset:5120
	ds_read_b128 v[230:233], v144 offset:6144
	ds_read_b128 v[234:237], v144 offset:7168
	global_load_lds_dwordx4 v136, s[64:65]
	s_add_i32 m0, s23, 0xe000
	s_nop 0
	global_load_lds_dwordx4 v138, s[64:65]
	s_waitcnt vmcnt(8)
	s_waitcnt lgkmcnt(0)
	s_setprio 1
	s_waitcnt lgkmcnt(0)
	v_mfma_f32_16x16x32_bf16 v[126:129], v[146:149], v[206:209], v[126:129]
	v_mfma_f32_16x16x32_bf16 v[122:125], v[154:157], v[206:209], v[122:125]
	v_mfma_f32_16x16x32_bf16 v[110:113], v[146:149], v[214:217], v[110:113]
	v_mfma_f32_16x16x32_bf16 v[106:109], v[154:157], v[214:217], v[106:109]
	s_barrier
	v_mfma_f32_16x16x32_bf16 v[94:97], v[146:149], v[222:225], v[94:97]
	v_mfma_f32_16x16x32_bf16 v[90:93], v[154:157], v[222:225], v[90:93]
	v_mfma_f32_16x16x32_bf16 v[78:81], v[146:149], v[230:233], v[78:81]
	v_mfma_f32_16x16x32_bf16 v[74:77], v[154:157], v[230:233], v[74:77]
	v_mfma_f32_16x16x32_bf16 v[126:129], v[150:153], v[210:213], v[126:129]
	v_mfma_f32_16x16x32_bf16 v[122:125], v[158:161], v[210:213], v[122:125]
	v_mfma_f32_16x16x32_bf16 v[110:113], v[150:153], v[218:221], v[110:113]
	v_mfma_f32_16x16x32_bf16 v[106:109], v[158:161], v[218:221], v[106:109]
	v_mfma_f32_16x16x32_bf16 v[94:97], v[150:153], v[226:229], v[94:97]
	v_mfma_f32_16x16x32_bf16 v[90:93], v[158:161], v[226:229], v[90:93]
	v_mfma_f32_16x16x32_bf16 v[78:81], v[150:153], v[234:237], v[78:81]
	v_mfma_f32_16x16x32_bf16 v[74:77], v[158:161], v[234:237], v[74:77]
	s_setprio 0
	s_setprio 1
	v_mfma_f32_16x16x32_bf16 v[118:121], v[162:165], v[206:209], v[118:121]
	v_mfma_f32_16x16x32_bf16 v[114:117], v[182:185], v[206:209], v[114:117]
	v_mfma_f32_16x16x32_bf16 v[102:105], v[162:165], v[214:217], v[102:105]
	v_mfma_f32_16x16x32_bf16 v[98:101], v[182:185], v[214:217], v[98:101]
	v_mfma_f32_16x16x32_bf16 v[86:89], v[162:165], v[222:225], v[86:89]
	v_mfma_f32_16x16x32_bf16 v[82:85], v[182:185], v[222:225], v[82:85]
	v_mfma_f32_16x16x32_bf16 v[70:73], v[162:165], v[230:233], v[70:73]
	v_mfma_f32_16x16x32_bf16 v[66:69], v[182:185], v[230:233], v[66:69]
	v_mfma_f32_16x16x32_bf16 v[118:121], v[178:181], v[210:213], v[118:121]
	v_mfma_f32_16x16x32_bf16 v[114:117], v[186:189], v[210:213], v[114:117]
	v_mfma_f32_16x16x32_bf16 v[102:105], v[178:181], v[218:221], v[102:105]
	v_mfma_f32_16x16x32_bf16 v[98:101], v[186:189], v[218:221], v[98:101]
	v_mfma_f32_16x16x32_bf16 v[86:89], v[178:181], v[226:229], v[86:89]
	v_mfma_f32_16x16x32_bf16 v[82:85], v[186:189], v[226:229], v[82:85]
	v_mfma_f32_16x16x32_bf16 v[70:73], v[178:181], v[234:237], v[70:73]
	v_mfma_f32_16x16x32_bf16 v[66:69], v[186:189], v[234:237], v[66:69]
	s_setprio 0
	s_barrier
	s_add_i32 s46, s48, s72
	s_mov_b32 m0, s46
	ds_read_b128 v[206:209], v144 offset:16384
	ds_read_b128 v[210:213], v144 offset:17408
	ds_read_b128 v[214:217], v144 offset:18432
	ds_read_b128 v[218:221], v144 offset:19456
	ds_read_b128 v[222:225], v144 offset:20480
	ds_read_b128 v[226:229], v144 offset:21504
	ds_read_b128 v[230:233], v144 offset:22528
	ds_read_b128 v[234:237], v144 offset:23552
	global_load_lds_dwordx4 v166, s[60:61]
	s_add_i32 m0, s46, 0x2000
	s_add_u32 s46, s60, 0x80000
	s_addc_u32 s47, s61, 0
	s_add_i32 s48, s49, s72
	global_load_lds_dwordx4 v134, s[60:61]
	s_mov_b32 m0, s48
	s_nop 0
	global_load_lds_dwordx4 v166, s[46:47]
	s_add_i32 m0, s48, 0x2000
	s_nop 0
	global_load_lds_dwordx4 v134, s[46:47]
	s_mov_b32 m0, s23
	s_nop 0
	global_load_lds_dwordx4 v130, s[66:67]
	s_mov_b32 m0, s73
	s_nop 0
	global_load_lds_dwordx4 v132, s[66:67]
	s_waitcnt vmcnt(8)
	s_waitcnt lgkmcnt(0)
	s_setprio 1
	s_waitcnt lgkmcnt(0)
	v_mfma_f32_16x16x32_bf16 v[62:65], v[146:149], v[206:209], v[62:65]
	v_mfma_f32_16x16x32_bf16 v[58:61], v[154:157], v[206:209], v[58:61]
	v_mfma_f32_16x16x32_bf16 v[46:49], v[146:149], v[214:217], v[46:49]
	v_mfma_f32_16x16x32_bf16 v[42:45], v[154:157], v[214:217], v[42:45]
	s_barrier
	v_mfma_f32_16x16x32_bf16 v[30:33], v[146:149], v[222:225], v[30:33]
	v_mfma_f32_16x16x32_bf16 v[26:29], v[154:157], v[222:225], v[26:29]
	v_mfma_f32_16x16x32_bf16 v[14:17], v[146:149], v[230:233], v[14:17]
	v_mfma_f32_16x16x32_bf16 v[10:13], v[154:157], v[230:233], v[10:13]
	v_mfma_f32_16x16x32_bf16 v[62:65], v[150:153], v[210:213], v[62:65]
	v_mfma_f32_16x16x32_bf16 v[58:61], v[158:161], v[210:213], v[58:61]
	v_mfma_f32_16x16x32_bf16 v[46:49], v[150:153], v[218:221], v[46:49]
	v_mfma_f32_16x16x32_bf16 v[42:45], v[158:161], v[218:221], v[42:45]
	v_mfma_f32_16x16x32_bf16 v[30:33], v[150:153], v[226:229], v[30:33]
	v_mfma_f32_16x16x32_bf16 v[26:29], v[158:161], v[226:229], v[26:29]
	v_mfma_f32_16x16x32_bf16 v[14:17], v[150:153], v[234:237], v[14:17]
	v_mfma_f32_16x16x32_bf16 v[10:13], v[158:161], v[234:237], v[10:13]
	s_setprio 0
	s_setprio 1
	v_mfma_f32_16x16x32_bf16 v[54:57], v[162:165], v[206:209], v[54:57]
	v_mfma_f32_16x16x32_bf16 v[50:53], v[182:185], v[206:209], v[50:53]
	v_mfma_f32_16x16x32_bf16 v[38:41], v[162:165], v[214:217], v[38:41]
	v_mfma_f32_16x16x32_bf16 v[34:37], v[182:185], v[214:217], v[34:37]
	v_mfma_f32_16x16x32_bf16 v[22:25], v[162:165], v[222:225], v[22:25]
	v_mfma_f32_16x16x32_bf16 v[18:21], v[182:185], v[222:225], v[18:21]
	v_mfma_f32_16x16x32_bf16 v[6:9], v[162:165], v[230:233], v[6:9]
	v_mfma_f32_16x16x32_bf16 v[2:5], v[182:185], v[230:233], v[2:5]
	v_mfma_f32_16x16x32_bf16 v[54:57], v[178:181], v[210:213], v[54:57]
	v_mfma_f32_16x16x32_bf16 v[50:53], v[186:189], v[210:213], v[50:53]
	v_mfma_f32_16x16x32_bf16 v[38:41], v[178:181], v[218:221], v[38:41]
	v_mfma_f32_16x16x32_bf16 v[34:37], v[186:189], v[218:221], v[34:37]
	v_mfma_f32_16x16x32_bf16 v[22:25], v[178:181], v[226:229], v[22:25]
	v_mfma_f32_16x16x32_bf16 v[18:21], v[186:189], v[226:229], v[18:21]
	v_mfma_f32_16x16x32_bf16 v[6:9], v[178:181], v[234:237], v[6:9]
	v_mfma_f32_16x16x32_bf16 v[2:5], v[186:189], v[234:237], v[2:5]
	s_setprio 0
	s_barrier
	s_add_i32 s48, 0, 0x18000
	v_add_u32_e32 v145, s48, v142
	s_add_i32 s49, 0, 0x1c000
	ds_read_b128 v[146:149], v145
	ds_read_b128 v[150:153], v145 offset:1024
	ds_read_b128 v[154:157], v145 offset:2048
	ds_read_b128 v[158:161], v145 offset:3072
	v_add_u32_e32 v145, s49, v142
	ds_read_b128 v[162:165], v145
	ds_read_b128 v[178:181], v145 offset:1024
	ds_read_b128 v[182:185], v145 offset:2048
	ds_read_b128 v[186:189], v145 offset:3072
	s_add_u32 s46, s66, 0x80000
	s_addc_u32 s47, s67, 0
	s_mov_b32 m0, s74
	ds_read_b128 v[206:209], v144 offset:32768
	ds_read_b128 v[210:213], v144 offset:33792
	ds_read_b128 v[214:217], v144 offset:34816
	ds_read_b128 v[218:221], v144 offset:35840
	ds_read_b128 v[222:225], v144 offset:36864
	ds_read_b128 v[226:229], v144 offset:37888
	ds_read_b128 v[230:233], v144 offset:38912
	ds_read_b128 v[234:237], v144 offset:39936
	global_load_lds_dwordx4 v130, s[46:47]
	s_mov_b32 m0, s75
	s_nop 0
	global_load_lds_dwordx4 v132, s[46:47]
	s_waitcnt vmcnt(8)
	s_waitcnt lgkmcnt(0)
	s_setprio 1
	s_waitcnt lgkmcnt(0)
	v_mfma_f32_16x16x32_bf16 v[126:129], v[146:149], v[206:209], v[126:129]
	v_mfma_f32_16x16x32_bf16 v[122:125], v[154:157], v[206:209], v[122:125]
	v_mfma_f32_16x16x32_bf16 v[110:113], v[146:149], v[214:217], v[110:113]
	v_mfma_f32_16x16x32_bf16 v[106:109], v[154:157], v[214:217], v[106:109]
	s_barrier
	v_mfma_f32_16x16x32_bf16 v[94:97], v[146:149], v[222:225], v[94:97]
	v_mfma_f32_16x16x32_bf16 v[90:93], v[154:157], v[222:225], v[90:93]
	v_mfma_f32_16x16x32_bf16 v[78:81], v[146:149], v[230:233], v[78:81]
	v_mfma_f32_16x16x32_bf16 v[74:77], v[154:157], v[230:233], v[74:77]
	v_mfma_f32_16x16x32_bf16 v[126:129], v[150:153], v[210:213], v[126:129]
	v_mfma_f32_16x16x32_bf16 v[122:125], v[158:161], v[210:213], v[122:125]
	v_mfma_f32_16x16x32_bf16 v[110:113], v[150:153], v[218:221], v[110:113]
	v_mfma_f32_16x16x32_bf16 v[106:109], v[158:161], v[218:221], v[106:109]
	v_mfma_f32_16x16x32_bf16 v[94:97], v[150:153], v[226:229], v[94:97]
	v_mfma_f32_16x16x32_bf16 v[90:93], v[158:161], v[226:229], v[90:93]
	v_mfma_f32_16x16x32_bf16 v[78:81], v[150:153], v[234:237], v[78:81]
	v_mfma_f32_16x16x32_bf16 v[74:77], v[158:161], v[234:237], v[74:77]
	s_setprio 0
	s_setprio 1
	v_mfma_f32_16x16x32_bf16 v[118:121], v[162:165], v[206:209], v[118:121]
	v_mfma_f32_16x16x32_bf16 v[114:117], v[182:185], v[206:209], v[114:117]
	v_mfma_f32_16x16x32_bf16 v[102:105], v[162:165], v[214:217], v[102:105]
	v_mfma_f32_16x16x32_bf16 v[98:101], v[182:185], v[214:217], v[98:101]
	v_mfma_f32_16x16x32_bf16 v[86:89], v[162:165], v[222:225], v[86:89]
	v_mfma_f32_16x16x32_bf16 v[82:85], v[182:185], v[222:225], v[82:85]
	v_mfma_f32_16x16x32_bf16 v[70:73], v[162:165], v[230:233], v[70:73]
	v_mfma_f32_16x16x32_bf16 v[66:69], v[182:185], v[230:233], v[66:69]
	v_mfma_f32_16x16x32_bf16 v[118:121], v[178:181], v[210:213], v[118:121]
	v_mfma_f32_16x16x32_bf16 v[114:117], v[186:189], v[210:213], v[114:117]
	v_mfma_f32_16x16x32_bf16 v[102:105], v[178:181], v[218:221], v[102:105]
	v_mfma_f32_16x16x32_bf16 v[98:101], v[186:189], v[218:221], v[98:101]
	v_mfma_f32_16x16x32_bf16 v[86:89], v[178:181], v[226:229], v[86:89]
	v_mfma_f32_16x16x32_bf16 v[82:85], v[186:189], v[226:229], v[82:85]
	v_mfma_f32_16x16x32_bf16 v[70:73], v[178:181], v[234:237], v[70:73]
	v_mfma_f32_16x16x32_bf16 v[66:69], v[186:189], v[234:237], v[66:69]
	s_setprio 0
	s_barrier
	s_add_i32 s46, s48, s72
	s_mov_b32 m0, s46
	ds_read_b128 v[206:209], v144 offset:49152
	ds_read_b128 v[210:213], v144 offset:50176
	ds_read_b128 v[214:217], v144 offset:51200
	ds_read_b128 v[218:221], v144 offset:52224
	ds_read_b128 v[222:225], v144 offset:53248
	ds_read_b128 v[226:229], v144 offset:54272
	ds_read_b128 v[230:233], v144 offset:55296
	ds_read_b128 v[234:237], v144 offset:56320
	s_add_u32 s100, s60, 128
	s_addc_u32 s101, s61, 0
	global_load_lds_dwordx4 v166, s[100:101]
	s_add_i32 m0, s46, 0x2000
	s_add_u32 s46, s60, 0x80080
	s_addc_u32 s47, s61, 0
	s_add_i32 s48, s49, s72
	s_add_u32 s100, s60, 128
	s_addc_u32 s101, s61, 0
	global_load_lds_dwordx4 v134, s[100:101]
	s_mov_b32 m0, s48
	s_nop 0
	global_load_lds_dwordx4 v166, s[46:47]
	s_add_i32 m0, s48, 0x2000
	s_nop 0
	global_load_lds_dwordx4 v134, s[46:47]
	s_mov_b32 m0, s76
	s_nop 0
	s_add_u32 s100, s66, 128
	s_addc_u32 s101, s67, 0
	global_load_lds_dwordx4 v130, s[100:101]
	s_mov_b32 m0, s77
	s_nop 0
	s_add_u32 s100, s66, 128
	s_addc_u32 s101, s67, 0
	global_load_lds_dwordx4 v132, s[100:101]
	s_waitcnt vmcnt(8)
	s_waitcnt lgkmcnt(0)
	s_setprio 1
	s_waitcnt lgkmcnt(0)
	v_mfma_f32_16x16x32_bf16 v[62:65], v[146:149], v[206:209], v[62:65]
	v_mfma_f32_16x16x32_bf16 v[58:61], v[154:157], v[206:209], v[58:61]
	v_mfma_f32_16x16x32_bf16 v[46:49], v[146:149], v[214:217], v[46:49]
	v_mfma_f32_16x16x32_bf16 v[42:45], v[154:157], v[214:217], v[42:45]
	s_barrier
	v_mfma_f32_16x16x32_bf16 v[30:33], v[146:149], v[222:225], v[30:33]
	v_mfma_f32_16x16x32_bf16 v[26:29], v[154:157], v[222:225], v[26:29]
	v_mfma_f32_16x16x32_bf16 v[14:17], v[146:149], v[230:233], v[14:17]
	v_mfma_f32_16x16x32_bf16 v[10:13], v[154:157], v[230:233], v[10:13]
	v_mfma_f32_16x16x32_bf16 v[62:65], v[150:153], v[210:213], v[62:65]
	v_mfma_f32_16x16x32_bf16 v[58:61], v[158:161], v[210:213], v[58:61]
	v_mfma_f32_16x16x32_bf16 v[46:49], v[150:153], v[218:221], v[46:49]
	v_mfma_f32_16x16x32_bf16 v[42:45], v[158:161], v[218:221], v[42:45]
	v_mfma_f32_16x16x32_bf16 v[30:33], v[150:153], v[226:229], v[30:33]
	v_mfma_f32_16x16x32_bf16 v[26:29], v[158:161], v[226:229], v[26:29]
	v_mfma_f32_16x16x32_bf16 v[14:17], v[150:153], v[234:237], v[14:17]
	v_mfma_f32_16x16x32_bf16 v[10:13], v[158:161], v[234:237], v[10:13]
	s_setprio 0
	s_setprio 1
	v_mfma_f32_16x16x32_bf16 v[54:57], v[162:165], v[206:209], v[54:57]
	v_mfma_f32_16x16x32_bf16 v[50:53], v[182:185], v[206:209], v[50:53]
	v_mfma_f32_16x16x32_bf16 v[38:41], v[162:165], v[214:217], v[38:41]
	v_mfma_f32_16x16x32_bf16 v[34:37], v[182:185], v[214:217], v[34:37]
	v_mfma_f32_16x16x32_bf16 v[22:25], v[162:165], v[222:225], v[22:25]
	v_mfma_f32_16x16x32_bf16 v[18:21], v[182:185], v[222:225], v[18:21]
	v_mfma_f32_16x16x32_bf16 v[6:9], v[162:165], v[230:233], v[6:9]
	v_mfma_f32_16x16x32_bf16 v[2:5], v[182:185], v[230:233], v[2:5]
	v_mfma_f32_16x16x32_bf16 v[54:57], v[178:181], v[210:213], v[54:57]
	v_mfma_f32_16x16x32_bf16 v[50:53], v[186:189], v[210:213], v[50:53]
	v_mfma_f32_16x16x32_bf16 v[38:41], v[178:181], v[218:221], v[38:41]
	v_mfma_f32_16x16x32_bf16 v[34:37], v[186:189], v[218:221], v[34:37]
	v_mfma_f32_16x16x32_bf16 v[22:25], v[178:181], v[226:229], v[22:25]
	v_mfma_f32_16x16x32_bf16 v[18:21], v[186:189], v[226:229], v[18:21]
	v_mfma_f32_16x16x32_bf16 v[6:9], v[178:181], v[234:237], v[6:9]
	v_mfma_f32_16x16x32_bf16 v[2:5], v[186:189], v[234:237], v[2:5]
	s_setprio 0
	s_barrier
	s_add_i32 s84, s84, 2
	s_add_u32 s64, s64, 0x100
	s_addc_u32 s65, s65, 0
	s_add_u32 s82, s82, 0x100
	s_addc_u32 s83, s83, 0
	s_cmp_gt_u32 s84, 29
	s_cbranch_scc0 .LBB0_1035
	s_and_b64 vcc, exec, s[10:11]
	s_cbranch_vccz .LBB0_1038
	s_barrier

.LBB0_1112:
	s_add_u32 s46, s64, 0xffe00080
	s_addc_u32 s47, s65, -1
	s_add_i32 s48, 0, 0x10000
	s_cmpk_eq_i32 s84, 0x7c
	s_cselect_b32 s67, s19, s47
	s_cselect_b32 s66, s80, s46
	s_cselect_b32 s61, s17, s83
	s_cselect_b32 s60, s81, s82
	s_add_i32 s49, 0, 0x14000
	v_add_u32_e32 v142, s48, v182
	v_add_u32_e32 v164, s49, v182
	ds_read_b128 v[130:133], v142
	ds_read_b128 v[134:137], v142 offset:1024
	ds_read_b128 v[138:141], v142 offset:2048
	ds_read_b128 v[142:145], v142 offset:3072
	ds_read_b128 v[146:149], v164
	ds_read_b128 v[160:163], v164 offset:1024
	ds_read_b128 v[178:181], v164 offset:2048
	ds_read_b128 v[186:189], v164 offset:3072
	s_add_i32 m0, s63, 0xc000
	ds_read_b128 v[206:209], v184
	ds_read_b128 v[210:213], v184 offset:1024
	ds_read_b128 v[214:217], v184 offset:2048
	ds_read_b128 v[218:221], v184 offset:3072
	ds_read_b128 v[222:225], v184 offset:4096
	ds_read_b128 v[226:229], v184 offset:5120
	ds_read_b128 v[230:233], v184 offset:6144
	ds_read_b128 v[234:237], v184 offset:7168
	global_load_lds_dwordx4 v156, s[64:65]
	s_add_i32 m0, s63, 0xe000
	s_nop 0
	global_load_lds_dwordx4 v158, s[64:65]
	s_waitcnt vmcnt(8)
	s_waitcnt lgkmcnt(0)
	s_setprio 1
	s_waitcnt lgkmcnt(0)
	v_mfma_f32_16x16x32_bf16 v[126:129], v[130:133], v[206:209], v[126:129]
	v_mfma_f32_16x16x32_bf16 v[122:125], v[138:141], v[206:209], v[122:125]
	v_mfma_f32_16x16x32_bf16 v[118:121], v[130:133], v[214:217], v[118:121]
	v_mfma_f32_16x16x32_bf16 v[114:117], v[138:141], v[214:217], v[114:117]
	s_barrier
	v_mfma_f32_16x16x32_bf16 v[94:97], v[130:133], v[222:225], v[94:97]
	v_mfma_f32_16x16x32_bf16 v[90:93], v[138:141], v[222:225], v[90:93]
	v_mfma_f32_16x16x32_bf16 v[82:85], v[130:133], v[230:233], v[82:85]
	v_mfma_f32_16x16x32_bf16 v[74:77], v[138:141], v[230:233], v[74:77]
	v_mfma_f32_16x16x32_bf16 v[126:129], v[134:137], v[210:213], v[126:129]
	v_mfma_f32_16x16x32_bf16 v[122:125], v[142:145], v[210:213], v[122:125]
	v_mfma_f32_16x16x32_bf16 v[118:121], v[134:137], v[218:221], v[118:121]
	v_mfma_f32_16x16x32_bf16 v[114:117], v[142:145], v[218:221], v[114:117]
	v_mfma_f32_16x16x32_bf16 v[94:97], v[134:137], v[226:229], v[94:97]
	v_mfma_f32_16x16x32_bf16 v[90:93], v[142:145], v[226:229], v[90:93]
	v_mfma_f32_16x16x32_bf16 v[82:85], v[134:137], v[234:237], v[82:85]
	v_mfma_f32_16x16x32_bf16 v[74:77], v[142:145], v[234:237], v[74:77]
	s_setprio 0
	s_setprio 1
	v_mfma_f32_16x16x32_bf16 v[110:113], v[146:149], v[206:209], v[110:113]
	v_mfma_f32_16x16x32_bf16 v[106:109], v[178:181], v[206:209], v[106:109]
	v_mfma_f32_16x16x32_bf16 v[102:105], v[146:149], v[214:217], v[102:105]
	v_mfma_f32_16x16x32_bf16 v[98:101], v[178:181], v[214:217], v[98:101]
	v_mfma_f32_16x16x32_bf16 v[86:89], v[146:149], v[222:225], v[86:89]
	v_mfma_f32_16x16x32_bf16 v[78:81], v[178:181], v[222:225], v[78:81]
	v_mfma_f32_16x16x32_bf16 v[70:73], v[146:149], v[230:233], v[70:73]
	v_mfma_f32_16x16x32_bf16 v[66:69], v[178:181], v[230:233], v[66:69]
	v_mfma_f32_16x16x32_bf16 v[110:113], v[160:163], v[210:213], v[110:113]
	v_mfma_f32_16x16x32_bf16 v[106:109], v[186:189], v[210:213], v[106:109]
	v_mfma_f32_16x16x32_bf16 v[102:105], v[160:163], v[218:221], v[102:105]
	v_mfma_f32_16x16x32_bf16 v[98:101], v[186:189], v[218:221], v[98:101]
	v_mfma_f32_16x16x32_bf16 v[86:89], v[160:163], v[226:229], v[86:89]
	v_mfma_f32_16x16x32_bf16 v[78:81], v[186:189], v[226:229], v[78:81]
	v_mfma_f32_16x16x32_bf16 v[70:73], v[160:163], v[234:237], v[70:73]
	v_mfma_f32_16x16x32_bf16 v[66:69], v[186:189], v[234:237], v[66:69]
	s_setprio 0
	s_barrier
	s_add_i32 s46, s48, s72
	s_mov_b32 m0, s46
	ds_read_b128 v[206:209], v184 offset:16384
	ds_read_b128 v[210:213], v184 offset:17408
	ds_read_b128 v[214:217], v184 offset:18432
	ds_read_b128 v[218:221], v184 offset:19456
	ds_read_b128 v[222:225], v184 offset:20480
	ds_read_b128 v[226:229], v184 offset:21504
	ds_read_b128 v[230:233], v184 offset:22528
	ds_read_b128 v[234:237], v184 offset:23552
	global_load_lds_dwordx4 v166, s[60:61]
	s_add_i32 m0, s46, 0x2000
	s_add_u32 s46, s60, 0x200000
	s_addc_u32 s47, s61, 0
	s_add_i32 s48, s49, s72
	global_load_lds_dwordx4 v154, s[60:61]
	s_mov_b32 m0, s48
	s_nop 0
	global_load_lds_dwordx4 v166, s[46:47]
	s_add_i32 m0, s48, 0x2000
	s_nop 0
	global_load_lds_dwordx4 v154, s[46:47]
	s_mov_b32 m0, s63
	s_nop 0
	global_load_lds_dwordx4 v150, s[66:67]
	s_mov_b32 m0, s73
	s_nop 0
	global_load_lds_dwordx4 v152, s[66:67]
	s_waitcnt vmcnt(8)
	s_waitcnt lgkmcnt(0)
	s_setprio 1
	s_waitcnt lgkmcnt(0)
	v_mfma_f32_16x16x32_bf16 v[62:65], v[130:133], v[206:209], v[62:65]
	v_mfma_f32_16x16x32_bf16 v[58:61], v[138:141], v[206:209], v[58:61]
	v_mfma_f32_16x16x32_bf16 v[50:53], v[130:133], v[214:217], v[50:53]
	v_mfma_f32_16x16x32_bf16 v[42:45], v[138:141], v[214:217], v[42:45]
	s_barrier
	v_mfma_f32_16x16x32_bf16 v[34:37], v[130:133], v[222:225], v[34:37]
	v_mfma_f32_16x16x32_bf16 v[26:29], v[138:141], v[222:225], v[26:29]
	v_mfma_f32_16x16x32_bf16 v[18:21], v[130:133], v[230:233], v[18:21]
	v_mfma_f32_16x16x32_bf16 v[10:13], v[138:141], v[230:233], v[10:13]
	v_mfma_f32_16x16x32_bf16 v[62:65], v[134:137], v[210:213], v[62:65]
	v_mfma_f32_16x16x32_bf16 v[58:61], v[142:145], v[210:213], v[58:61]
	v_mfma_f32_16x16x32_bf16 v[50:53], v[134:137], v[218:221], v[50:53]
	v_mfma_f32_16x16x32_bf16 v[42:45], v[142:145], v[218:221], v[42:45]
	v_mfma_f32_16x16x32_bf16 v[34:37], v[134:137], v[226:229], v[34:37]
	v_mfma_f32_16x16x32_bf16 v[26:29], v[142:145], v[226:229], v[26:29]
	v_mfma_f32_16x16x32_bf16 v[18:21], v[134:137], v[234:237], v[18:21]
	v_mfma_f32_16x16x32_bf16 v[10:13], v[142:145], v[234:237], v[10:13]
	s_setprio 0
	s_setprio 1
	v_mfma_f32_16x16x32_bf16 v[54:57], v[146:149], v[206:209], v[54:57]
	v_mfma_f32_16x16x32_bf16 v[46:49], v[178:181], v[206:209], v[46:49]
	v_mfma_f32_16x16x32_bf16 v[38:41], v[146:149], v[214:217], v[38:41]
	v_mfma_f32_16x16x32_bf16 v[30:33], v[178:181], v[214:217], v[30:33]
	v_mfma_f32_16x16x32_bf16 v[22:25], v[146:149], v[222:225], v[22:25]
	v_mfma_f32_16x16x32_bf16 v[14:17], v[178:181], v[222:225], v[14:17]
	v_mfma_f32_16x16x32_bf16 v[6:9], v[146:149], v[230:233], v[6:9]
	v_mfma_f32_16x16x32_bf16 v[2:5], v[178:181], v[230:233], v[2:5]
	v_mfma_f32_16x16x32_bf16 v[54:57], v[160:163], v[210:213], v[54:57]
	v_mfma_f32_16x16x32_bf16 v[46:49], v[186:189], v[210:213], v[46:49]
	v_mfma_f32_16x16x32_bf16 v[38:41], v[160:163], v[218:221], v[38:41]
	v_mfma_f32_16x16x32_bf16 v[30:33], v[186:189], v[218:221], v[30:33]
	v_mfma_f32_16x16x32_bf16 v[22:25], v[160:163], v[226:229], v[22:25]
	v_mfma_f32_16x16x32_bf16 v[14:17], v[186:189], v[226:229], v[14:17]
	v_mfma_f32_16x16x32_bf16 v[6:9], v[160:163], v[234:237], v[6:9]
	v_mfma_f32_16x16x32_bf16 v[2:5], v[186:189], v[234:237], v[2:5]
	s_setprio 0
	s_barrier
	s_add_i32 s48, 0, 0x18000
	s_add_i32 s49, 0, 0x1c000
	v_add_u32_e32 v142, s48, v182
	v_add_u32_e32 v185, s49, v182
	ds_read_b128 v[130:133], v142
	ds_read_b128 v[134:137], v142 offset:1024
	ds_read_b128 v[138:141], v142 offset:2048
	ds_read_b128 v[142:145], v142 offset:3072
	ds_read_b128 v[146:149], v185
	ds_read_b128 v[160:163], v185 offset:1024
	ds_read_b128 v[178:181], v185 offset:2048
	ds_read_b128 v[186:189], v185 offset:3072
	s_add_u32 s46, s66, 0x200000
	s_addc_u32 s47, s67, 0
	s_mov_b32 m0, s74
	ds_read_b128 v[206:209], v184 offset:32768
	ds_read_b128 v[210:213], v184 offset:33792
	ds_read_b128 v[214:217], v184 offset:34816
	ds_read_b128 v[218:221], v184 offset:35840
	ds_read_b128 v[222:225], v184 offset:36864
	ds_read_b128 v[226:229], v184 offset:37888
	ds_read_b128 v[230:233], v184 offset:38912
	ds_read_b128 v[234:237], v184 offset:39936
	global_load_lds_dwordx4 v150, s[46:47]
	s_mov_b32 m0, s75
	s_nop 0
	global_load_lds_dwordx4 v152, s[46:47]
	s_waitcnt vmcnt(8)
	s_waitcnt lgkmcnt(0)
	s_setprio 1
	s_waitcnt lgkmcnt(0)
	v_mfma_f32_16x16x32_bf16 v[126:129], v[130:133], v[206:209], v[126:129]
	v_mfma_f32_16x16x32_bf16 v[122:125], v[138:141], v[206:209], v[122:125]
	v_mfma_f32_16x16x32_bf16 v[118:121], v[130:133], v[214:217], v[118:121]
	v_mfma_f32_16x16x32_bf16 v[114:117], v[138:141], v[214:217], v[114:117]
	s_barrier
	v_mfma_f32_16x16x32_bf16 v[94:97], v[130:133], v[222:225], v[94:97]
	v_mfma_f32_16x16x32_bf16 v[90:93], v[138:141], v[222:225], v[90:93]
	v_mfma_f32_16x16x32_bf16 v[82:85], v[130:133], v[230:233], v[82:85]
	v_mfma_f32_16x16x32_bf16 v[74:77], v[138:141], v[230:233], v[74:77]
	v_mfma_f32_16x16x32_bf16 v[126:129], v[134:137], v[210:213], v[126:129]
	v_mfma_f32_16x16x32_bf16 v[122:125], v[142:145], v[210:213], v[122:125]
	v_mfma_f32_16x16x32_bf16 v[118:121], v[134:137], v[218:221], v[118:121]
	v_mfma_f32_16x16x32_bf16 v[114:117], v[142:145], v[218:221], v[114:117]
	v_mfma_f32_16x16x32_bf16 v[94:97], v[134:137], v[226:229], v[94:97]
	v_mfma_f32_16x16x32_bf16 v[90:93], v[142:145], v[226:229], v[90:93]
	v_mfma_f32_16x16x32_bf16 v[82:85], v[134:137], v[234:237], v[82:85]
	v_mfma_f32_16x16x32_bf16 v[74:77], v[142:145], v[234:237], v[74:77]
	s_setprio 0
	s_setprio 1
	v_mfma_f32_16x16x32_bf16 v[110:113], v[146:149], v[206:209], v[110:113]
	v_mfma_f32_16x16x32_bf16 v[106:109], v[178:181], v[206:209], v[106:109]
	v_mfma_f32_16x16x32_bf16 v[102:105], v[146:149], v[214:217], v[102:105]
	v_mfma_f32_16x16x32_bf16 v[98:101], v[178:181], v[214:217], v[98:101]
	v_mfma_f32_16x16x32_bf16 v[86:89], v[146:149], v[222:225], v[86:89]
	v_mfma_f32_16x16x32_bf16 v[78:81], v[178:181], v[222:225], v[78:81]
	v_mfma_f32_16x16x32_bf16 v[70:73], v[146:149], v[230:233], v[70:73]
	v_mfma_f32_16x16x32_bf16 v[66:69], v[178:181], v[230:233], v[66:69]
	v_mfma_f32_16x16x32_bf16 v[110:113], v[160:163], v[210:213], v[110:113]
	v_mfma_f32_16x16x32_bf16 v[106:109], v[186:189], v[210:213], v[106:109]
	v_mfma_f32_16x16x32_bf16 v[102:105], v[160:163], v[218:221], v[102:105]
	v_mfma_f32_16x16x32_bf16 v[98:101], v[186:189], v[218:221], v[98:101]
	v_mfma_f32_16x16x32_bf16 v[86:89], v[160:163], v[226:229], v[86:89]
	v_mfma_f32_16x16x32_bf16 v[78:81], v[186:189], v[226:229], v[78:81]
	v_mfma_f32_16x16x32_bf16 v[70:73], v[160:163], v[234:237], v[70:73]
	v_mfma_f32_16x16x32_bf16 v[66:69], v[186:189], v[234:237], v[66:69]
	s_setprio 0
	s_barrier
	s_add_i32 s46, s48, s72
	s_mov_b32 m0, s46
	ds_read_b128 v[206:209], v184 offset:49152
	ds_read_b128 v[210:213], v184 offset:50176
	ds_read_b128 v[214:217], v184 offset:51200
	ds_read_b128 v[218:221], v184 offset:52224
	ds_read_b128 v[222:225], v184 offset:53248
	ds_read_b128 v[226:229], v184 offset:54272
	ds_read_b128 v[230:233], v184 offset:55296
	ds_read_b128 v[234:237], v184 offset:56320
	s_add_u32 s100, s60, 128
	s_addc_u32 s101, s61, 0
	global_load_lds_dwordx4 v166, s[100:101]
	s_add_i32 m0, s46, 0x2000
	s_add_u32 s46, s60, 0x200080
	s_addc_u32 s47, s61, 0
	s_add_i32 s48, s49, s72
	s_add_u32 s100, s60, 128
	s_addc_u32 s101, s61, 0
	global_load_lds_dwordx4 v154, s[100:101]
	s_mov_b32 m0, s48
	s_nop 0
	global_load_lds_dwordx4 v166, s[46:47]
	s_add_i32 m0, s48, 0x2000
	s_nop 0
	global_load_lds_dwordx4 v154, s[46:47]
	s_mov_b32 m0, s76
	s_nop 0
	s_add_u32 s100, s66, 128
	s_addc_u32 s101, s67, 0
	global_load_lds_dwordx4 v150, s[100:101]
	s_mov_b32 m0, s77
	s_nop 0
	s_add_u32 s100, s66, 128
	s_addc_u32 s101, s67, 0
	global_load_lds_dwordx4 v152, s[100:101]
	s_waitcnt vmcnt(8)
	s_waitcnt lgkmcnt(0)
	s_setprio 1
	s_waitcnt lgkmcnt(0)
	v_mfma_f32_16x16x32_bf16 v[62:65], v[130:133], v[206:209], v[62:65]
	v_mfma_f32_16x16x32_bf16 v[58:61], v[138:141], v[206:209], v[58:61]
	v_mfma_f32_16x16x32_bf16 v[50:53], v[130:133], v[214:217], v[50:53]
	v_mfma_f32_16x16x32_bf16 v[42:45], v[138:141], v[214:217], v[42:45]
	s_barrier
	v_mfma_f32_16x16x32_bf16 v[34:37], v[130:133], v[222:225], v[34:37]
	v_mfma_f32_16x16x32_bf16 v[26:29], v[138:141], v[222:225], v[26:29]
	v_mfma_f32_16x16x32_bf16 v[18:21], v[130:133], v[230:233], v[18:21]
	v_mfma_f32_16x16x32_bf16 v[10:13], v[138:141], v[230:233], v[10:13]
	v_mfma_f32_16x16x32_bf16 v[62:65], v[134:137], v[210:213], v[62:65]
	v_mfma_f32_16x16x32_bf16 v[58:61], v[142:145], v[210:213], v[58:61]
	v_mfma_f32_16x16x32_bf16 v[50:53], v[134:137], v[218:221], v[50:53]
	v_mfma_f32_16x16x32_bf16 v[42:45], v[142:145], v[218:221], v[42:45]
	v_mfma_f32_16x16x32_bf16 v[34:37], v[134:137], v[226:229], v[34:37]
	v_mfma_f32_16x16x32_bf16 v[26:29], v[142:145], v[226:229], v[26:29]
	v_mfma_f32_16x16x32_bf16 v[18:21], v[134:137], v[234:237], v[18:21]
	v_mfma_f32_16x16x32_bf16 v[10:13], v[142:145], v[234:237], v[10:13]
	s_setprio 0
	s_setprio 1
	v_mfma_f32_16x16x32_bf16 v[54:57], v[146:149], v[206:209], v[54:57]
	v_mfma_f32_16x16x32_bf16 v[46:49], v[178:181], v[206:209], v[46:49]
	v_mfma_f32_16x16x32_bf16 v[38:41], v[146:149], v[214:217], v[38:41]
	v_mfma_f32_16x16x32_bf16 v[30:33], v[178:181], v[214:217], v[30:33]
	v_mfma_f32_16x16x32_bf16 v[22:25], v[146:149], v[222:225], v[22:25]
	v_mfma_f32_16x16x32_bf16 v[14:17], v[178:181], v[222:225], v[14:17]
	v_mfma_f32_16x16x32_bf16 v[6:9], v[146:149], v[230:233], v[6:9]
	v_mfma_f32_16x16x32_bf16 v[2:5], v[178:181], v[230:233], v[2:5]
	v_mfma_f32_16x16x32_bf16 v[54:57], v[160:163], v[210:213], v[54:57]
	v_mfma_f32_16x16x32_bf16 v[46:49], v[186:189], v[210:213], v[46:49]
	v_mfma_f32_16x16x32_bf16 v[38:41], v[160:163], v[218:221], v[38:41]
	v_mfma_f32_16x16x32_bf16 v[30:33], v[186:189], v[218:221], v[30:33]
	v_mfma_f32_16x16x32_bf16 v[22:25], v[160:163], v[226:229], v[22:25]
	v_mfma_f32_16x16x32_bf16 v[14:17], v[186:189], v[226:229], v[14:17]
	v_mfma_f32_16x16x32_bf16 v[6:9], v[160:163], v[234:237], v[6:9]
	v_mfma_f32_16x16x32_bf16 v[2:5], v[186:189], v[234:237], v[2:5]
	s_setprio 0
	s_barrier
	s_add_i32 s84, s84, 2
	s_add_u32 s64, s64, 0x100
	s_addc_u32 s65, s65, 0
	s_add_u32 s82, s82, 0x100
	s_addc_u32 s83, s83, 0
	s_cmpk_gt_u32 s84, 0x7d
	s_cbranch_scc0 .LBB0_1112
	s_and_b64 vcc, exec, s[12:13]
	s_cbranch_vccz .LBB0_1115
	s_barrier

.LBB0_1138:
	s_add_u32 s46, s62, 0xffe00080
	s_addc_u32 s47, s63, -1
	s_add_i32 s48, 0, 0x10000
	s_cmpk_eq_i32 s82, 0x7c
	s_cselect_b32 s65, s17, s47
	s_cselect_b32 s64, s78, s46
	s_cselect_b32 s61, s13, s81
	s_cselect_b32 s60, s79, s80
	s_add_i32 s49, 0, 0x14000
	v_add_u32_e32 v142, s48, v186
	v_add_u32_e32 v164, s49, v186
	ds_read_b128 v[130:133], v142
	ds_read_b128 v[134:137], v142 offset:1024
	ds_read_b128 v[138:141], v142 offset:2048
	ds_read_b128 v[142:145], v142 offset:3072
	ds_read_b128 v[146:149], v164
	ds_read_b128 v[160:163], v164 offset:1024
	ds_read_b128 v[178:181], v164 offset:2048
	ds_read_b128 v[182:185], v164 offset:3072
	s_add_i32 m0, s71, 0xc000
	ds_read_b128 v[206:209], v188
	ds_read_b128 v[210:213], v188 offset:1024
	ds_read_b128 v[214:217], v188 offset:2048
	ds_read_b128 v[218:221], v188 offset:3072
	ds_read_b128 v[222:225], v188 offset:4096
	ds_read_b128 v[226:229], v188 offset:5120
	ds_read_b128 v[230:233], v188 offset:6144
	ds_read_b128 v[234:237], v188 offset:7168
	global_load_lds_dwordx4 v156, s[62:63]
	s_add_i32 m0, s71, 0xe000
	s_nop 0
	global_load_lds_dwordx4 v158, s[62:63]
	s_waitcnt vmcnt(8)
	s_waitcnt lgkmcnt(0)
	s_setprio 1
	s_waitcnt lgkmcnt(0)
	v_mfma_f32_16x16x32_bf16 v[126:129], v[130:133], v[206:209], v[126:129]
	v_mfma_f32_16x16x32_bf16 v[122:125], v[138:141], v[206:209], v[122:125]
	v_mfma_f32_16x16x32_bf16 v[118:121], v[130:133], v[214:217], v[118:121]
	v_mfma_f32_16x16x32_bf16 v[110:113], v[138:141], v[214:217], v[110:113]
	s_barrier
	v_mfma_f32_16x16x32_bf16 v[94:97], v[130:133], v[222:225], v[94:97]
	v_mfma_f32_16x16x32_bf16 v[90:93], v[138:141], v[222:225], v[90:93]
	v_mfma_f32_16x16x32_bf16 v[82:85], v[130:133], v[230:233], v[82:85]
	v_mfma_f32_16x16x32_bf16 v[74:77], v[138:141], v[230:233], v[74:77]
	v_mfma_f32_16x16x32_bf16 v[126:129], v[134:137], v[210:213], v[126:129]
	v_mfma_f32_16x16x32_bf16 v[122:125], v[142:145], v[210:213], v[122:125]
	v_mfma_f32_16x16x32_bf16 v[118:121], v[134:137], v[218:221], v[118:121]
	v_mfma_f32_16x16x32_bf16 v[110:113], v[142:145], v[218:221], v[110:113]
	v_mfma_f32_16x16x32_bf16 v[94:97], v[134:137], v[226:229], v[94:97]
	v_mfma_f32_16x16x32_bf16 v[90:93], v[142:145], v[226:229], v[90:93]
	v_mfma_f32_16x16x32_bf16 v[82:85], v[134:137], v[234:237], v[82:85]
	v_mfma_f32_16x16x32_bf16 v[74:77], v[142:145], v[234:237], v[74:77]
	s_setprio 0
	s_setprio 1
	v_mfma_f32_16x16x32_bf16 v[114:117], v[146:149], v[206:209], v[114:117]
	v_mfma_f32_16x16x32_bf16 v[106:109], v[178:181], v[206:209], v[106:109]
	v_mfma_f32_16x16x32_bf16 v[102:105], v[146:149], v[214:217], v[102:105]
	v_mfma_f32_16x16x32_bf16 v[98:101], v[178:181], v[214:217], v[98:101]
	v_mfma_f32_16x16x32_bf16 v[86:89], v[146:149], v[222:225], v[86:89]
	v_mfma_f32_16x16x32_bf16 v[78:81], v[178:181], v[222:225], v[78:81]
	v_mfma_f32_16x16x32_bf16 v[70:73], v[146:149], v[230:233], v[70:73]
	v_mfma_f32_16x16x32_bf16 v[66:69], v[178:181], v[230:233], v[66:69]
	v_mfma_f32_16x16x32_bf16 v[114:117], v[160:163], v[210:213], v[114:117]
	v_mfma_f32_16x16x32_bf16 v[106:109], v[182:185], v[210:213], v[106:109]
	v_mfma_f32_16x16x32_bf16 v[102:105], v[160:163], v[218:221], v[102:105]
	v_mfma_f32_16x16x32_bf16 v[98:101], v[182:185], v[218:221], v[98:101]
	v_mfma_f32_16x16x32_bf16 v[86:89], v[160:163], v[226:229], v[86:89]
	v_mfma_f32_16x16x32_bf16 v[78:81], v[182:185], v[226:229], v[78:81]
	v_mfma_f32_16x16x32_bf16 v[70:73], v[160:163], v[234:237], v[70:73]
	v_mfma_f32_16x16x32_bf16 v[66:69], v[182:185], v[234:237], v[66:69]
	s_setprio 0
	s_barrier
	s_add_i32 s46, s48, s70
	s_mov_b32 m0, s46
	ds_read_b128 v[206:209], v188 offset:16384
	ds_read_b128 v[210:213], v188 offset:17408
	ds_read_b128 v[214:217], v188 offset:18432
	ds_read_b128 v[218:221], v188 offset:19456
	ds_read_b128 v[222:225], v188 offset:20480
	ds_read_b128 v[226:229], v188 offset:21504
	ds_read_b128 v[230:233], v188 offset:22528
	ds_read_b128 v[234:237], v188 offset:23552
	global_load_lds_dwordx4 v166, s[60:61]
	s_add_i32 m0, s46, 0x2000
	s_add_u32 s46, s60, 0x200000
	s_addc_u32 s47, s61, 0
	s_add_i32 s48, s49, s70
	global_load_lds_dwordx4 v154, s[60:61]
	s_mov_b32 m0, s48
	s_nop 0
	global_load_lds_dwordx4 v166, s[46:47]
	s_add_i32 m0, s48, 0x2000
	s_nop 0
	global_load_lds_dwordx4 v154, s[46:47]
	s_mov_b32 m0, s71
	s_nop 0
	global_load_lds_dwordx4 v150, s[64:65]
	s_mov_b32 m0, s72
	s_nop 0
	global_load_lds_dwordx4 v152, s[64:65]
	s_waitcnt vmcnt(8)
	s_waitcnt lgkmcnt(0)
	s_setprio 1
	s_waitcnt lgkmcnt(0)
	v_mfma_f32_16x16x32_bf16 v[62:65], v[130:133], v[206:209], v[62:65]
	v_mfma_f32_16x16x32_bf16 v[58:61], v[138:141], v[206:209], v[58:61]
	v_mfma_f32_16x16x32_bf16 v[50:53], v[130:133], v[214:217], v[50:53]
	v_mfma_f32_16x16x32_bf16 v[42:45], v[138:141], v[214:217], v[42:45]
	s_barrier
	v_mfma_f32_16x16x32_bf16 v[34:37], v[130:133], v[222:225], v[34:37]
	v_mfma_f32_16x16x32_bf16 v[26:29], v[138:141], v[222:225], v[26:29]
	v_mfma_f32_16x16x32_bf16 v[18:21], v[130:133], v[230:233], v[18:21]
	v_mfma_f32_16x16x32_bf16 v[10:13], v[138:141], v[230:233], v[10:13]
	v_mfma_f32_16x16x32_bf16 v[62:65], v[134:137], v[210:213], v[62:65]
	v_mfma_f32_16x16x32_bf16 v[58:61], v[142:145], v[210:213], v[58:61]
	v_mfma_f32_16x16x32_bf16 v[50:53], v[134:137], v[218:221], v[50:53]
	v_mfma_f32_16x16x32_bf16 v[42:45], v[142:145], v[218:221], v[42:45]
	v_mfma_f32_16x16x32_bf16 v[34:37], v[134:137], v[226:229], v[34:37]
	v_mfma_f32_16x16x32_bf16 v[26:29], v[142:145], v[226:229], v[26:29]
	v_mfma_f32_16x16x32_bf16 v[18:21], v[134:137], v[234:237], v[18:21]
	v_mfma_f32_16x16x32_bf16 v[10:13], v[142:145], v[234:237], v[10:13]
	s_setprio 0
	s_setprio 1
	v_mfma_f32_16x16x32_bf16 v[54:57], v[146:149], v[206:209], v[54:57]
	v_mfma_f32_16x16x32_bf16 v[46:49], v[178:181], v[206:209], v[46:49]
	v_mfma_f32_16x16x32_bf16 v[38:41], v[146:149], v[214:217], v[38:41]
	v_mfma_f32_16x16x32_bf16 v[30:33], v[178:181], v[214:217], v[30:33]
	v_mfma_f32_16x16x32_bf16 v[22:25], v[146:149], v[222:225], v[22:25]
	v_mfma_f32_16x16x32_bf16 v[14:17], v[178:181], v[222:225], v[14:17]
	v_mfma_f32_16x16x32_bf16 v[6:9], v[146:149], v[230:233], v[6:9]
	v_mfma_f32_16x16x32_bf16 v[2:5], v[178:181], v[230:233], v[2:5]
	v_mfma_f32_16x16x32_bf16 v[54:57], v[160:163], v[210:213], v[54:57]
	v_mfma_f32_16x16x32_bf16 v[46:49], v[182:185], v[210:213], v[46:49]
	v_mfma_f32_16x16x32_bf16 v[38:41], v[160:163], v[218:221], v[38:41]
	v_mfma_f32_16x16x32_bf16 v[30:33], v[182:185], v[218:221], v[30:33]
	v_mfma_f32_16x16x32_bf16 v[22:25], v[160:163], v[226:229], v[22:25]
	v_mfma_f32_16x16x32_bf16 v[14:17], v[182:185], v[226:229], v[14:17]
	v_mfma_f32_16x16x32_bf16 v[6:9], v[160:163], v[234:237], v[6:9]
	v_mfma_f32_16x16x32_bf16 v[2:5], v[182:185], v[234:237], v[2:5]
	s_setprio 0
	s_barrier
	s_add_i32 s48, 0, 0x18000
	s_add_i32 s49, 0, 0x1c000
	v_add_u32_e32 v142, s48, v186
	v_add_u32_e32 v182, s49, v186
	ds_read_b128 v[130:133], v142
	ds_read_b128 v[134:137], v142 offset:1024
	ds_read_b128 v[138:141], v142 offset:2048
	ds_read_b128 v[142:145], v142 offset:3072
	ds_read_b128 v[146:149], v182
	ds_read_b128 v[160:163], v182 offset:1024
	ds_read_b128 v[178:181], v182 offset:2048
	ds_read_b128 v[182:185], v182 offset:3072
	s_add_u32 s46, s64, 0x200000
	s_addc_u32 s47, s65, 0
	s_mov_b32 m0, s73
	ds_read_b128 v[206:209], v188 offset:32768
	ds_read_b128 v[210:213], v188 offset:33792
	ds_read_b128 v[214:217], v188 offset:34816
	ds_read_b128 v[218:221], v188 offset:35840
	ds_read_b128 v[222:225], v188 offset:36864
	ds_read_b128 v[226:229], v188 offset:37888
	ds_read_b128 v[230:233], v188 offset:38912
	ds_read_b128 v[234:237], v188 offset:39936
	global_load_lds_dwordx4 v150, s[46:47]
	s_mov_b32 m0, s74
	s_nop 0
	global_load_lds_dwordx4 v152, s[46:47]
	s_waitcnt vmcnt(8)
	s_waitcnt lgkmcnt(0)
	s_setprio 1
	s_waitcnt lgkmcnt(0)
	v_mfma_f32_16x16x32_bf16 v[126:129], v[130:133], v[206:209], v[126:129]
	v_mfma_f32_16x16x32_bf16 v[122:125], v[138:141], v[206:209], v[122:125]
	v_mfma_f32_16x16x32_bf16 v[118:121], v[130:133], v[214:217], v[118:121]
	v_mfma_f32_16x16x32_bf16 v[110:113], v[138:141], v[214:217], v[110:113]
	s_barrier
	v_mfma_f32_16x16x32_bf16 v[94:97], v[130:133], v[222:225], v[94:97]
	v_mfma_f32_16x16x32_bf16 v[90:93], v[138:141], v[222:225], v[90:93]
	v_mfma_f32_16x16x32_bf16 v[82:85], v[130:133], v[230:233], v[82:85]
	v_mfma_f32_16x16x32_bf16 v[74:77], v[138:141], v[230:233], v[74:77]
	v_mfma_f32_16x16x32_bf16 v[126:129], v[134:137], v[210:213], v[126:129]
	v_mfma_f32_16x16x32_bf16 v[122:125], v[142:145], v[210:213], v[122:125]
	v_mfma_f32_16x16x32_bf16 v[118:121], v[134:137], v[218:221], v[118:121]
	v_mfma_f32_16x16x32_bf16 v[110:113], v[142:145], v[218:221], v[110:113]
	v_mfma_f32_16x16x32_bf16 v[94:97], v[134:137], v[226:229], v[94:97]
	v_mfma_f32_16x16x32_bf16 v[90:93], v[142:145], v[226:229], v[90:93]
	v_mfma_f32_16x16x32_bf16 v[82:85], v[134:137], v[234:237], v[82:85]
	v_mfma_f32_16x16x32_bf16 v[74:77], v[142:145], v[234:237], v[74:77]
	s_setprio 0
	s_setprio 1
	v_mfma_f32_16x16x32_bf16 v[114:117], v[146:149], v[206:209], v[114:117]
	v_mfma_f32_16x16x32_bf16 v[106:109], v[178:181], v[206:209], v[106:109]
	v_mfma_f32_16x16x32_bf16 v[102:105], v[146:149], v[214:217], v[102:105]
	v_mfma_f32_16x16x32_bf16 v[98:101], v[178:181], v[214:217], v[98:101]
	v_mfma_f32_16x16x32_bf16 v[86:89], v[146:149], v[222:225], v[86:89]
	v_mfma_f32_16x16x32_bf16 v[78:81], v[178:181], v[222:225], v[78:81]
	v_mfma_f32_16x16x32_bf16 v[70:73], v[146:149], v[230:233], v[70:73]
	v_mfma_f32_16x16x32_bf16 v[66:69], v[178:181], v[230:233], v[66:69]
	v_mfma_f32_16x16x32_bf16 v[114:117], v[160:163], v[210:213], v[114:117]
	v_mfma_f32_16x16x32_bf16 v[106:109], v[182:185], v[210:213], v[106:109]
	v_mfma_f32_16x16x32_bf16 v[102:105], v[160:163], v[218:221], v[102:105]
	v_mfma_f32_16x16x32_bf16 v[98:101], v[182:185], v[218:221], v[98:101]
	v_mfma_f32_16x16x32_bf16 v[86:89], v[160:163], v[226:229], v[86:89]
	v_mfma_f32_16x16x32_bf16 v[78:81], v[182:185], v[226:229], v[78:81]
	v_mfma_f32_16x16x32_bf16 v[70:73], v[160:163], v[234:237], v[70:73]
	v_mfma_f32_16x16x32_bf16 v[66:69], v[182:185], v[234:237], v[66:69]
	s_setprio 0
	s_barrier
	s_add_i32 s46, s48, s70
	s_mov_b32 m0, s46
	ds_read_b128 v[206:209], v188 offset:49152
	ds_read_b128 v[210:213], v188 offset:50176
	ds_read_b128 v[214:217], v188 offset:51200
	ds_read_b128 v[218:221], v188 offset:52224
	ds_read_b128 v[222:225], v188 offset:53248
	ds_read_b128 v[226:229], v188 offset:54272
	ds_read_b128 v[230:233], v188 offset:55296
	ds_read_b128 v[234:237], v188 offset:56320
	s_add_u32 s100, s60, 128
	s_addc_u32 s101, s61, 0
	global_load_lds_dwordx4 v166, s[100:101]
	s_add_i32 m0, s46, 0x2000
	s_add_u32 s46, s60, 0x200080
	s_addc_u32 s47, s61, 0
	s_add_i32 s48, s49, s70
	s_add_u32 s100, s60, 128
	s_addc_u32 s101, s61, 0
	global_load_lds_dwordx4 v154, s[100:101]
	s_mov_b32 m0, s48
	s_nop 0
	global_load_lds_dwordx4 v166, s[46:47]
	s_add_i32 m0, s48, 0x2000
	s_nop 0
	global_load_lds_dwordx4 v154, s[46:47]
	s_mov_b32 m0, s75
	s_nop 0
	s_add_u32 s100, s64, 128
	s_addc_u32 s101, s65, 0
	global_load_lds_dwordx4 v150, s[100:101]
	s_mov_b32 m0, s76
	s_nop 0
	s_add_u32 s100, s64, 128
	s_addc_u32 s101, s65, 0
	global_load_lds_dwordx4 v152, s[100:101]
	s_waitcnt vmcnt(8)
	s_waitcnt lgkmcnt(0)
	s_setprio 1
	s_waitcnt lgkmcnt(0)
	v_mfma_f32_16x16x32_bf16 v[62:65], v[130:133], v[206:209], v[62:65]
	v_mfma_f32_16x16x32_bf16 v[58:61], v[138:141], v[206:209], v[58:61]
	v_mfma_f32_16x16x32_bf16 v[50:53], v[130:133], v[214:217], v[50:53]
	v_mfma_f32_16x16x32_bf16 v[42:45], v[138:141], v[214:217], v[42:45]
	s_barrier
	v_mfma_f32_16x16x32_bf16 v[34:37], v[130:133], v[222:225], v[34:37]
	v_mfma_f32_16x16x32_bf16 v[26:29], v[138:141], v[222:225], v[26:29]
	v_mfma_f32_16x16x32_bf16 v[18:21], v[130:133], v[230:233], v[18:21]
	v_mfma_f32_16x16x32_bf16 v[10:13], v[138:141], v[230:233], v[10:13]
	v_mfma_f32_16x16x32_bf16 v[62:65], v[134:137], v[210:213], v[62:65]
	v_mfma_f32_16x16x32_bf16 v[58:61], v[142:145], v[210:213], v[58:61]
	v_mfma_f32_16x16x32_bf16 v[50:53], v[134:137], v[218:221], v[50:53]
	v_mfma_f32_16x16x32_bf16 v[42:45], v[142:145], v[218:221], v[42:45]
	v_mfma_f32_16x16x32_bf16 v[34:37], v[134:137], v[226:229], v[34:37]
	v_mfma_f32_16x16x32_bf16 v[26:29], v[142:145], v[226:229], v[26:29]
	v_mfma_f32_16x16x32_bf16 v[18:21], v[134:137], v[234:237], v[18:21]
	v_mfma_f32_16x16x32_bf16 v[10:13], v[142:145], v[234:237], v[10:13]
	s_setprio 0
	s_setprio 1
	v_mfma_f32_16x16x32_bf16 v[54:57], v[146:149], v[206:209], v[54:57]
	v_mfma_f32_16x16x32_bf16 v[46:49], v[178:181], v[206:209], v[46:49]
	v_mfma_f32_16x16x32_bf16 v[38:41], v[146:149], v[214:217], v[38:41]
	v_mfma_f32_16x16x32_bf16 v[30:33], v[178:181], v[214:217], v[30:33]
	v_mfma_f32_16x16x32_bf16 v[22:25], v[146:149], v[222:225], v[22:25]
	v_mfma_f32_16x16x32_bf16 v[14:17], v[178:181], v[222:225], v[14:17]
	v_mfma_f32_16x16x32_bf16 v[6:9], v[146:149], v[230:233], v[6:9]
	v_mfma_f32_16x16x32_bf16 v[2:5], v[178:181], v[230:233], v[2:5]
	v_mfma_f32_16x16x32_bf16 v[54:57], v[160:163], v[210:213], v[54:57]
	v_mfma_f32_16x16x32_bf16 v[46:49], v[182:185], v[210:213], v[46:49]
	v_mfma_f32_16x16x32_bf16 v[38:41], v[160:163], v[218:221], v[38:41]
	v_mfma_f32_16x16x32_bf16 v[30:33], v[182:185], v[218:221], v[30:33]
	v_mfma_f32_16x16x32_bf16 v[22:25], v[160:163], v[226:229], v[22:25]
	v_mfma_f32_16x16x32_bf16 v[14:17], v[182:185], v[226:229], v[14:17]
	v_mfma_f32_16x16x32_bf16 v[6:9], v[160:163], v[234:237], v[6:9]
	v_mfma_f32_16x16x32_bf16 v[2:5], v[182:185], v[234:237], v[2:5]
	s_setprio 0
	s_barrier
	s_add_i32 s82, s82, 2
	s_add_u32 s62, s62, 0x100
	s_addc_u32 s63, s63, 0
	s_add_u32 s80, s80, 0x100
	s_addc_u32 s81, s81, 0
	s_cmpk_gt_u32 s82, 0x7d
	s_cbranch_scc0 .LBB0_1138
	s_and_b64 vcc, exec, s[10:11]
	s_cbranch_vccz .LBB0_1141
	s_barrier

	.amdhsa_kernel _Z10fwd_kernel4Args
		.amdhsa_group_segment_fixed_size 0
		.amdhsa_private_segment_fixed_size 0
		.amdhsa_kernarg_size 440
		.amdhsa_user_sgpr_count 2
		.amdhsa_user_sgpr_dispatch_ptr 0
		.amdhsa_user_sgpr_queue_ptr 0
		.amdhsa_user_sgpr_kernarg_segment_ptr 1
		.amdhsa_user_sgpr_dispatch_id 0
		.amdhsa_user_sgpr_kernarg_preload_length 0
		.amdhsa_user_sgpr_kernarg_preload_offset 0
		.amdhsa_user_sgpr_private_segment_size 0
		.amdhsa_uses_dynamic_stack 0
		.amdhsa_enable_private_segment 0
		.amdhsa_system_sgpr_workgroup_id_x 1
		.amdhsa_system_sgpr_workgroup_id_y 0
		.amdhsa_system_sgpr_workgroup_id_z 0
		.amdhsa_system_sgpr_workgroup_info 0
		.amdhsa_system_vgpr_workitem_id 0
		.amdhsa_next_free_vgpr 256
		.amdhsa_next_free_sgpr 102
		.amdhsa_accum_offset 256
		.amdhsa_reserve_vcc 1
		.amdhsa_float_round_mode_32 0
		.amdhsa_float_round_mode_16_64 0
		.amdhsa_float_denorm_mode_32 3
		.amdhsa_float_denorm_mode_16_64 3
		.amdhsa_dx10_clamp 1
		.amdhsa_ieee_mode 1
		.amdhsa_fp16_overflow 0
		.amdhsa_tg_split 0
		.amdhsa_exception_fp_ieee_invalid_op 0
		.amdhsa_exception_fp_denorm_src 0
		.amdhsa_exception_fp_ieee_div_zero 0
		.amdhsa_exception_fp_ieee_overflow 0
		.amdhsa_exception_fp_ieee_underflow 0
		.amdhsa_exception_fp_ieee_inexact 0
		.amdhsa_exception_int_div_zero 0
	.end_amdhsa_kernel

amdhsa.kernels:
  - .agpr_count:     0
    .args:
      - .offset:         0
        .size:           184
        .value_kind:     by_value
      - .offset:         184
        .size:           4
        .value_kind:     hidden_block_count_x
      - .offset:         188
        .size:           4
        .value_kind:     hidden_block_count_y
      - .offset:         192
        .size:           4
        .value_kind:     hidden_block_count_z
      - .offset:         196
        .size:           2
        .value_kind:     hidden_group_size_x
      - .offset:         198
        .size:           2
        .value_kind:     hidden_group_size_y
      - .offset:         200
        .size:           2
        .value_kind:     hidden_group_size_z
      - .offset:         202
        .size:           2
        .value_kind:     hidden_remainder_x
      - .offset:         204
        .size:           2
        .value_kind:     hidden_remainder_y
      - .offset:         206
        .size:           2
        .value_kind:     hidden_remainder_z
      - .offset:         224
        .size:           8
        .value_kind:     hidden_global_offset_x
      - .offset:         232
        .size:           8
        .value_kind:     hidden_global_offset_y
      - .offset:         240
        .size:           8
        .value_kind:     hidden_global_offset_z
      - .offset:         248
        .size:           2
        .value_kind:     hidden_grid_dims
      - .offset:         304
        .size:           4
        .value_kind:     hidden_dynamic_lds_size
    .group_segment_fixed_size: 0
    .kernarg_segment_align: 8
    .kernarg_segment_size: 440
    .language:       OpenCL C
    .language_version:
      - 2
      - 0
    .max_flat_workgroup_size: 512
    .name:           _Z10fwd_kernel4Args
    .private_segment_fixed_size: 0
    .sgpr_count:     108
    .sgpr_spill_count: 24
    .symbol:         _Z10fwd_kernel4Args.kd
    .uniform_work_group_size: 1
    .uses_dynamic_stack: false
    .vgpr_count:     256
    .vgpr_spill_count: 0
    .wavefront_size: 64
